# nt cache hint on read-once streaming loads: x rows in P1 and the P4 epilogue, f32 weight loads in P0
# speedup vs baseline: 1.0360x; 1.0360x over previous
; __device__ __forceinline__ unsigned cvt_pk_bf16(float lo, float hi) { unsigned r; asm("v_cvt_pk_bf16_f32 %0, %1, %2" : "=v"(r) : "v"(lo), "v"(hi)); return r; }
; template <bool PERMW, bool PERM32>
; __device__ __forceinline__ void transpose_cvt(const float* __restrict__ src, bf16_t* __restrict__ dst, int K, int N, float* T, int& tile_ctr, int blk, int nblk) {
;     ...
;     for (int tl = tl0; tl < ntiles; tl += nblk) {
;         const int k0 = (tl % nkt) * 64, n0 = (tl / nkt) * 256;
;         { const int n4 = (tid & 63) * 4, sc = PERMW ? win_src_col(n0 + n4) : n0 + n4; f32x4 v[8];
; #pragma unroll
;           for (int i = 0; i < 8; ++i) { const int k = (tid >> 6) + 8 * i; v[i] = *(const f32x4*)(src + (size_t)(k0 + k) * N + sc); }
; #pragma unroll
;           for (int i = 0; i < 8; ++i) { const int k = (tid >> 6) + 8 * i; *(f32x4*)(T + k * 256 + (n4 ^ (((k >> 3) & 7) << 2))) = v[i]; } }
;         __syncthreads();
; #pragma unroll
;         for (int i = 0; i < 4; ++i) { const int pi = tid + 512 * i, q = pi & 7, nl = pi >> 3, x = PERM32 ? (nl & ~31) + perm32(nl & 31) : nl; const float* tp = T + (8 * q) * 256 + (x ^ (q << 2)); uint4 o;
;             o.x = cvt_pk_bf16(tp[0], tp[256]); o.y = cvt_pk_bf16(tp[512], tp[768]); o.z = cvt_pk_bf16(tp[1024], tp[1280]); o.w = cvt_pk_bf16(tp[1536], tp[1792]);
;             *(uint4*)(dst + (size_t)(n0 + nl) * K + k0 + 8 * q) = o; }
;         __syncthreads();
.LBB0_25:
	s_lshl_b32 s14, s73, 10
	s_sub_i32 s14, s70, s14
	v_add_u32_e32 v52, s14, v10
	v_ashrrev_i32_e32 v7, 31, v6
	v_lshl_add_u64 v[6:7], v[6:7], 2, s[16:17]
	v_add_u32_e32 v28, 8, v52
	v_add_u32_e32 v34, 16, v52
	v_add_u32_e32 v36, 24, v52
	v_add_u32_e32 v42, 32, v52
	v_add_u32_e32 v44, 40, v52
	v_add_u32_e32 v50, 48, v52
	v_mad_i64_i32 v[26:27], s[74:75], v52, s67, v[6:7]
	v_mad_i64_i32 v[30:31], s[74:75], v28, s67, v[6:7]
	v_mad_i64_i32 v[34:35], s[74:75], v34, s67, v[6:7]
	v_mad_i64_i32 v[38:39], s[74:75], v36, s67, v[6:7]
	v_mad_i64_i32 v[42:43], s[74:75], v42, s67, v[6:7]
	v_mad_i64_i32 v[46:47], s[74:75], v44, s67, v[6:7]
	v_mad_i64_i32 v[50:51], s[74:75], v50, s67, v[6:7]
	v_add_u32_e32 v52, 56, v52
	global_load_dwordx4 v[26:29], v[26:27], off nt
	s_nop 0
	global_load_dwordx4 v[30:33], v[30:31], off nt
	s_nop 0
	global_load_dwordx4 v[34:37], v[34:35], off nt
	s_nop 0
	global_load_dwordx4 v[38:41], v[38:39], off nt
	s_nop 0
	global_load_dwordx4 v[42:45], v[42:43], off nt
	s_nop 0
	global_load_dwordx4 v[46:49], v[46:47], off nt
	v_mad_i64_i32 v[6:7], s[74:75], v52, s67, v[6:7]
	global_load_dwordx4 v[50:53], v[50:51], off nt
	s_nop 0
	global_load_dwordx4 v[54:57], v[6:7], off nt
	v_add_u32_e32 v6, s72, v2
	v_add_u32_e32 v58, s72, v20
	v_add_u32_e32 v60, s72, v22
	v_ashrrev_i32_e32 v7, 31, v6
	s_ashr_i32 s15, s14, 31
	v_ashrrev_i32_e32 v59, 31, v58
	v_ashrrev_i32_e32 v61, 31, v60
	v_lshlrev_b64 v[6:7], 11, v[6:7]
	v_lshl_add_u64 v[62:63], s[14:15], 1, v[4:5]
	v_lshlrev_b64 v[58:59], 11, v[58:59]
	v_lshlrev_b64 v[60:61], 11, v[60:61]
	v_lshl_add_u64 v[6:7], v[62:63], 0, v[6:7]
	v_lshl_add_u64 v[58:59], v[62:63], 0, v[58:59]
	v_lshl_add_u64 v[60:61], v[62:63], 0, v[60:61]
	s_add_i32 s69, s69, s33
	s_add_i32 s70, s70, s71
	s_cmpk_lt_i32 s69, 0xa0
	s_waitcnt vmcnt(7)
	ds_write_b128 v12, v[26:29]
	s_waitcnt vmcnt(6)
	ds_write_b128 v13, v[30:33]
	s_waitcnt vmcnt(5)
	ds_write_b128 v14, v[34:37]
	s_waitcnt vmcnt(4)
	ds_write_b128 v15, v[38:41]
	s_waitcnt vmcnt(3)
	ds_write_b128 v16, v[42:45]
	s_waitcnt vmcnt(2)
	ds_write_b128 v17, v[46:49]
	s_waitcnt vmcnt(1)
	ds_write_b128 v18, v[50:53]
	s_waitcnt vmcnt(0)
	ds_write_b128 v19, v[54:57]
	s_waitcnt lgkmcnt(0)
	s_barrier
	ds_read2st64_b32 v[26:27], v11 offset1:4
	ds_read2st64_b32 v[28:29], v11 offset0:8 offset1:12
	ds_read2st64_b32 v[30:31], v11 offset0:16 offset1:20
	ds_read2st64_b32 v[32:33], v11 offset0:24 offset1:28
	ds_read2st64_b32 v[34:35], v21 offset1:4
	ds_read2st64_b32 v[36:37], v21 offset0:8 offset1:12
	ds_read2st64_b32 v[38:39], v21 offset0:16 offset1:20
	ds_read2st64_b32 v[40:41], v21 offset0:24 offset1:28
	ds_read2st64_b32 v[42:43], v23 offset1:4
	ds_read2st64_b32 v[44:45], v23 offset0:8 offset1:12
	ds_read2st64_b32 v[46:47], v23 offset0:16 offset1:20
	ds_read2st64_b32 v[48:49], v23 offset0:24 offset1:28
	ds_read2st64_b32 v[50:51], v25 offset1:4
	ds_read2st64_b32 v[52:53], v25 offset0:8 offset1:12
	ds_read2st64_b32 v[54:55], v25 offset0:16 offset1:20
	ds_read2st64_b32 v[56:57], v25 offset0:24 offset1:28
	s_waitcnt lgkmcnt(14)
	v_cvt_pk_bf16_f32 v26, v26, v27
	v_cvt_pk_bf16_f32 v27, v28, v29
	s_waitcnt lgkmcnt(13)
	v_cvt_pk_bf16_f32 v28, v30, v31
	s_waitcnt lgkmcnt(12)
	v_cvt_pk_bf16_f32 v29, v32, v33
	s_waitcnt lgkmcnt(11)
	v_cvt_pk_bf16_f32 v30, v34, v35
	s_waitcnt lgkmcnt(10)
	v_cvt_pk_bf16_f32 v31, v36, v37
	s_waitcnt lgkmcnt(9)
	v_cvt_pk_bf16_f32 v32, v38, v39
	s_waitcnt lgkmcnt(8)
	v_cvt_pk_bf16_f32 v33, v40, v41
	s_waitcnt lgkmcnt(7)
	v_cvt_pk_bf16_f32 v34, v42, v43
	s_waitcnt lgkmcnt(6)
	v_cvt_pk_bf16_f32 v35, v44, v45
	s_waitcnt lgkmcnt(5)
	v_cvt_pk_bf16_f32 v36, v46, v47
	s_waitcnt lgkmcnt(4)
	v_cvt_pk_bf16_f32 v37, v48, v49
	global_store_dwordx4 v[6:7], v[26:29], off
	global_store_dwordx4 v[58:59], v[30:33], off
	global_store_dwordx4 v[60:61], v[34:37], off
	v_add_u32_e32 v6, s72, v24
	v_ashrrev_i32_e32 v7, 31, v6
	v_lshlrev_b64 v[6:7], 11, v[6:7]
	v_lshl_add_u64 v[6:7], v[62:63], 0, v[6:7]
	s_waitcnt lgkmcnt(3)
	v_cvt_pk_bf16_f32 v26, v50, v51
	s_waitcnt lgkmcnt(2)
	v_cvt_pk_bf16_f32 v27, v52, v53
	s_waitcnt lgkmcnt(1)
	v_cvt_pk_bf16_f32 v28, v54, v55
	s_waitcnt lgkmcnt(0)
	v_cvt_pk_bf16_f32 v29, v56, v57
	global_store_dwordx4 v[6:7], v[26:29], off
	s_barrier
	s_cbranch_scc0 .LBB0_31

; __device__ __forceinline__ unsigned cvt_pk_bf16(float lo, float hi) { unsigned r; asm("v_cvt_pk_bf16_f32 %0, %1, %2" : "=v"(r) : "v"(lo), "v"(hi)); return r; }
; template <bool PERMW, bool PERM32>
; __device__ __forceinline__ void transpose_cvt(const float* __restrict__ src, bf16_t* __restrict__ dst, int K, int N, float* T, int& tile_ctr, int blk, int nblk) {
;     ...
;     for (int tl = tl0; tl < ntiles; tl += nblk) {
;         const int k0 = (tl % nkt) * 64, n0 = (tl / nkt) * 256;
;         { const int n4 = (tid & 63) * 4, sc = PERMW ? win_src_col(n0 + n4) : n0 + n4; f32x4 v[8];
; #pragma unroll
;           for (int i = 0; i < 8; ++i) { const int k = (tid >> 6) + 8 * i; v[i] = *(const f32x4*)(src + (size_t)(k0 + k) * N + sc); }
; #pragma unroll
;           for (int i = 0; i < 8; ++i) { const int k = (tid >> 6) + 8 * i; *(f32x4*)(T + k * 256 + (n4 ^ (((k >> 3) & 7) << 2))) = v[i]; } }
;         __syncthreads();
; #pragma unroll
;         for (int i = 0; i < 4; ++i) { const int pi = tid + 512 * i, q = pi & 7, nl = pi >> 3, x = PERM32 ? (nl & ~31) + perm32(nl & 31) : nl; const float* tp = T + (8 * q) * 256 + (x ^ (q << 2)); uint4 o;
;             o.x = cvt_pk_bf16(tp[0], tp[256]); o.y = cvt_pk_bf16(tp[512], tp[768]); o.z = cvt_pk_bf16(tp[1024], tp[1280]); o.w = cvt_pk_bf16(tp[1536], tp[1792]);
;             *(uint4*)(dst + (size_t)(n0 + nl) * K + k0 + 8 * q) = o; }
;         __syncthreads();
.LBB0_33:
	s_ashr_i32 s14, s69, 31
	s_lshr_b32 s14, s14, 28
	s_add_i32 s14, s69, s14
	s_ashr_i32 s14, s14, 4
	s_lshl_b32 s72, s14, 10
	s_lshl_b32 s15, s14, 8
	s_sub_i32 s14, s70, s72
	v_add_u32_e32 v24, s14, v6
	v_or_b32_e32 v22, s15, v1
	v_add_u32_e32 v26, 8, v24
	v_add_u32_e32 v28, 16, v24
	v_add_u32_e32 v30, 24, v24
	v_add_u32_e32 v32, 32, v24
	v_add_u32_e32 v34, 40, v24
	v_add_u32_e32 v36, 48, v24
	v_add_u32_e32 v38, 56, v24
	v_ashrrev_i32_e32 v23, 31, v22
	v_ashrrev_i32_e32 v25, 31, v24
	v_ashrrev_i32_e32 v27, 31, v26
	v_ashrrev_i32_e32 v29, 31, v28
	v_ashrrev_i32_e32 v31, 31, v30
	v_ashrrev_i32_e32 v33, 31, v32
	v_ashrrev_i32_e32 v35, 31, v34
	v_ashrrev_i32_e32 v37, 31, v36
	v_ashrrev_i32_e32 v39, 31, v38
	v_lshl_add_u64 v[22:23], v[22:23], 2, s[26:27]
	v_lshlrev_b64 v[24:25], 12, v[24:25]
	v_lshlrev_b64 v[26:27], 12, v[26:27]
	v_lshlrev_b64 v[28:29], 12, v[28:29]
	v_lshlrev_b64 v[30:31], 12, v[30:31]
	v_lshlrev_b64 v[32:33], 12, v[32:33]
	v_lshlrev_b64 v[34:35], 12, v[34:35]
	v_lshlrev_b64 v[36:37], 12, v[36:37]
	v_lshlrev_b64 v[38:39], 12, v[38:39]
	v_lshl_add_u64 v[24:25], v[22:23], 0, v[24:25]
	v_lshl_add_u64 v[26:27], v[22:23], 0, v[26:27]
	v_lshl_add_u64 v[40:41], v[22:23], 0, v[28:29]
	v_lshl_add_u64 v[42:43], v[22:23], 0, v[30:31]
	v_lshl_add_u64 v[44:45], v[22:23], 0, v[32:33]
	v_lshl_add_u64 v[46:47], v[22:23], 0, v[34:35]
	v_lshl_add_u64 v[48:49], v[22:23], 0, v[36:37]
	v_lshl_add_u64 v[50:51], v[22:23], 0, v[38:39]
	global_load_dwordx4 v[22:25], v[24:25], off nt
	s_nop 0
	global_load_dwordx4 v[26:29], v[26:27], off nt
	s_nop 0
	global_load_dwordx4 v[30:33], v[40:41], off nt
	global_load_dwordx4 v[34:37], v[42:43], off nt
	s_nop 0
	global_load_dwordx4 v[38:41], v[44:45], off nt
	s_nop 0
	global_load_dwordx4 v[42:45], v[46:47], off nt
	s_nop 0
	global_load_dwordx4 v[46:49], v[48:49], off nt
	s_nop 0
	global_load_dwordx4 v[50:53], v[50:51], off nt
	v_add_u32_e32 v54, s15, v2
	v_add_u32_e32 v56, s15, v16
	v_add_u32_e32 v58, s15, v18
	v_add_u32_e32 v60, s15, v20
	s_ashr_i32 s15, s14, 31
	v_ashrrev_i32_e32 v55, 31, v54
	s_add_i32 s69, s69, s33
	s_add_i32 s70, s70, s71
	v_ashrrev_i32_e32 v57, 31, v56
	v_ashrrev_i32_e32 v59, 31, v58
	v_ashrrev_i32_e32 v61, 31, v60
	v_lshl_add_u64 v[62:63], s[14:15], 1, v[4:5]
	v_lshlrev_b64 v[54:55], 11, v[54:55]
	v_lshlrev_b64 v[56:57], 11, v[56:57]
	v_lshlrev_b64 v[58:59], 11, v[58:59]
	v_lshlrev_b64 v[60:61], 11, v[60:61]
	s_cmp_lt_i32 s69, 64
	v_lshl_add_u64 v[54:55], v[62:63], 0, v[54:55]
	v_lshl_add_u64 v[56:57], v[62:63], 0, v[56:57]
	v_lshl_add_u64 v[58:59], v[62:63], 0, v[58:59]
	v_lshl_add_u64 v[60:61], v[62:63], 0, v[60:61]
	s_waitcnt vmcnt(7)
	ds_write_b128 v8, v[22:25]
	s_waitcnt vmcnt(6)
	ds_write_b128 v9, v[26:29]
	s_waitcnt vmcnt(5)
	ds_write_b128 v10, v[30:33]
	s_waitcnt vmcnt(4)
	ds_write_b128 v11, v[34:37]
	s_waitcnt vmcnt(3)
	ds_write_b128 v12, v[38:41]
	s_waitcnt vmcnt(2)
	ds_write_b128 v13, v[42:45]
	s_waitcnt vmcnt(1)
	ds_write_b128 v14, v[46:49]
	s_waitcnt vmcnt(0)
	ds_write_b128 v15, v[50:53]
	s_waitcnt lgkmcnt(0)
	s_barrier
	ds_read2st64_b32 v[22:23], v7 offset1:4
	ds_read2st64_b32 v[24:25], v7 offset0:8 offset1:12
	ds_read2st64_b32 v[26:27], v7 offset0:16 offset1:20
	ds_read2st64_b32 v[28:29], v7 offset0:24 offset1:28
	ds_read2st64_b32 v[30:31], v17 offset1:4
	ds_read2st64_b32 v[32:33], v17 offset0:8 offset1:12
	ds_read2st64_b32 v[34:35], v17 offset0:16 offset1:20
	ds_read2st64_b32 v[36:37], v17 offset0:24 offset1:28
	ds_read2st64_b32 v[38:39], v19 offset1:4
	ds_read2st64_b32 v[40:41], v19 offset0:8 offset1:12
	ds_read2st64_b32 v[42:43], v19 offset0:16 offset1:20
	ds_read2st64_b32 v[44:45], v19 offset0:24 offset1:28
	ds_read2st64_b32 v[46:47], v21 offset1:4
	ds_read2st64_b32 v[48:49], v21 offset0:8 offset1:12
	ds_read2st64_b32 v[50:51], v21 offset0:16 offset1:20
	ds_read2st64_b32 v[52:53], v21 offset0:24 offset1:28
	s_waitcnt lgkmcnt(14)
	v_cvt_pk_bf16_f32 v22, v22, v23
	v_cvt_pk_bf16_f32 v23, v24, v25
	s_waitcnt lgkmcnt(13)
	v_cvt_pk_bf16_f32 v24, v26, v27
	s_waitcnt lgkmcnt(12)
	v_cvt_pk_bf16_f32 v25, v28, v29
	s_waitcnt lgkmcnt(11)
	v_cvt_pk_bf16_f32 v26, v30, v31
	s_waitcnt lgkmcnt(10)
	v_cvt_pk_bf16_f32 v27, v32, v33
	s_waitcnt lgkmcnt(9)
	v_cvt_pk_bf16_f32 v28, v34, v35
	s_waitcnt lgkmcnt(8)
	v_cvt_pk_bf16_f32 v29, v36, v37
	s_waitcnt lgkmcnt(7)
	v_cvt_pk_bf16_f32 v30, v38, v39
	s_waitcnt lgkmcnt(6)
	v_cvt_pk_bf16_f32 v31, v40, v41
	s_waitcnt lgkmcnt(5)
	v_cvt_pk_bf16_f32 v32, v42, v43
	s_waitcnt lgkmcnt(4)
	v_cvt_pk_bf16_f32 v33, v44, v45
	s_waitcnt lgkmcnt(3)
	v_cvt_pk_bf16_f32 v34, v46, v47
	s_waitcnt lgkmcnt(2)
	v_cvt_pk_bf16_f32 v35, v48, v49
	s_waitcnt lgkmcnt(1)
	v_cvt_pk_bf16_f32 v36, v50, v51
	s_waitcnt lgkmcnt(0)
	v_cvt_pk_bf16_f32 v37, v52, v53
	global_store_dwordx4 v[54:55], v[22:25], off
	global_store_dwordx4 v[56:57], v[26:29], off
	global_store_dwordx4 v[58:59], v[30:33], off
	global_store_dwordx4 v[60:61], v[34:37], off
	s_barrier
	s_cbranch_scc1 .LBB0_33

; __device__ __forceinline__ unsigned cvt_pk_bf16(float lo, float hi) { unsigned r; asm("v_cvt_pk_bf16_f32 %0, %1, %2" : "=v"(r) : "v"(lo), "v"(hi)); return r; }
; template <bool PERMW, bool PERM32>
; __device__ __forceinline__ void transpose_cvt(const float* __restrict__ src, bf16_t* __restrict__ dst, int K, int N, float* T, int& tile_ctr, int blk, int nblk) {
;     ...
;     for (int tl = tl0; tl < ntiles; tl += nblk) {
;         const int k0 = (tl % nkt) * 64, n0 = (tl / nkt) * 256;
;         { const int n4 = (tid & 63) * 4, sc = PERMW ? win_src_col(n0 + n4) : n0 + n4; f32x4 v[8];
; #pragma unroll
;           for (int i = 0; i < 8; ++i) { const int k = (tid >> 6) + 8 * i; v[i] = *(const f32x4*)(src + (size_t)(k0 + k) * N + sc); }
; #pragma unroll
;           for (int i = 0; i < 8; ++i) { const int k = (tid >> 6) + 8 * i; *(f32x4*)(T + k * 256 + (n4 ^ (((k >> 3) & 7) << 2))) = v[i]; } }
;         __syncthreads();
; #pragma unroll
;         for (int i = 0; i < 4; ++i) { const int pi = tid + 512 * i, q = pi & 7, nl = pi >> 3, x = PERM32 ? (nl & ~31) + perm32(nl & 31) : nl; const float* tp = T + (8 * q) * 256 + (x ^ (q << 2)); uint4 o;
;             o.x = cvt_pk_bf16(tp[0], tp[256]); o.y = cvt_pk_bf16(tp[512], tp[768]); o.z = cvt_pk_bf16(tp[1024], tp[1280]); o.w = cvt_pk_bf16(tp[1536], tp[1792]);
;             *(uint4*)(dst + (size_t)(n0 + nl) * K + k0 + 8 * q) = o; }
;         __syncthreads();
.LBB0_36:
	s_ashr_i32 s14, s69, 31
	s_lshr_b32 s14, s14, 26
	s_add_i32 s14, s69, s14
	s_ashr_i32 s14, s14, 6
	s_lshl_b32 s72, s14, 12
	s_lshl_b32 s15, s14, 8
	s_sub_i32 s14, s70, s72
	v_add_u32_e32 v24, s14, v6
	v_or_b32_e32 v22, s15, v1
	v_add_u32_e32 v26, 8, v24
	v_add_u32_e32 v28, 16, v24
	v_add_u32_e32 v30, 24, v24
	v_add_u32_e32 v32, 32, v24
	v_add_u32_e32 v34, 40, v24
	v_add_u32_e32 v36, 48, v24
	v_add_u32_e32 v38, 56, v24
	v_ashrrev_i32_e32 v23, 31, v22
	v_ashrrev_i32_e32 v25, 31, v24
	v_ashrrev_i32_e32 v27, 31, v26
	v_ashrrev_i32_e32 v29, 31, v28
	v_ashrrev_i32_e32 v31, 31, v30
	v_ashrrev_i32_e32 v33, 31, v32
	v_ashrrev_i32_e32 v35, 31, v34
	v_ashrrev_i32_e32 v37, 31, v36
	v_ashrrev_i32_e32 v39, 31, v38
	v_lshl_add_u64 v[22:23], v[22:23], 2, s[52:53]
	v_lshlrev_b64 v[24:25], 12, v[24:25]
	v_lshlrev_b64 v[26:27], 12, v[26:27]
	v_lshlrev_b64 v[28:29], 12, v[28:29]
	v_lshlrev_b64 v[30:31], 12, v[30:31]
	v_lshlrev_b64 v[32:33], 12, v[32:33]
	v_lshlrev_b64 v[34:35], 12, v[34:35]
	v_lshlrev_b64 v[36:37], 12, v[36:37]
	v_lshlrev_b64 v[38:39], 12, v[38:39]
	v_lshl_add_u64 v[24:25], v[22:23], 0, v[24:25]
	v_lshl_add_u64 v[26:27], v[22:23], 0, v[26:27]
	v_lshl_add_u64 v[40:41], v[22:23], 0, v[28:29]
	v_lshl_add_u64 v[42:43], v[22:23], 0, v[30:31]
	v_lshl_add_u64 v[44:45], v[22:23], 0, v[32:33]
	v_lshl_add_u64 v[46:47], v[22:23], 0, v[34:35]
	v_lshl_add_u64 v[48:49], v[22:23], 0, v[36:37]
	v_lshl_add_u64 v[50:51], v[22:23], 0, v[38:39]
	global_load_dwordx4 v[22:25], v[24:25], off nt
	s_nop 0
	global_load_dwordx4 v[26:29], v[26:27], off nt
	s_nop 0
	global_load_dwordx4 v[30:33], v[40:41], off nt
	global_load_dwordx4 v[34:37], v[42:43], off nt
	s_nop 0
	global_load_dwordx4 v[38:41], v[44:45], off nt
	s_nop 0
	global_load_dwordx4 v[42:45], v[46:47], off nt
	s_nop 0
	global_load_dwordx4 v[46:49], v[48:49], off nt
	s_nop 0
	global_load_dwordx4 v[50:53], v[50:51], off nt
	v_add_u32_e32 v54, s15, v2
	v_add_u32_e32 v56, s15, v16
	v_add_u32_e32 v58, s15, v18
	v_add_u32_e32 v60, s15, v20
	s_ashr_i32 s15, s14, 31
	v_ashrrev_i32_e32 v55, 31, v54
	s_add_i32 s69, s69, s33
	s_add_i32 s70, s70, s71
	v_ashrrev_i32_e32 v57, 31, v56
	v_ashrrev_i32_e32 v59, 31, v58
	v_ashrrev_i32_e32 v61, 31, v60
	v_lshl_add_u64 v[62:63], s[14:15], 1, v[4:5]
	v_lshlrev_b64 v[54:55], 13, v[54:55]
	v_lshlrev_b64 v[56:57], 13, v[56:57]
	v_lshlrev_b64 v[58:59], 13, v[58:59]
	v_lshlrev_b64 v[60:61], 13, v[60:61]
	s_cmpk_lt_i32 s69, 0x100
	v_lshl_add_u64 v[54:55], v[62:63], 0, v[54:55]
	v_lshl_add_u64 v[56:57], v[62:63], 0, v[56:57]
	v_lshl_add_u64 v[58:59], v[62:63], 0, v[58:59]
	v_lshl_add_u64 v[60:61], v[62:63], 0, v[60:61]
	s_waitcnt vmcnt(7)
	ds_write_b128 v8, v[22:25]
	s_waitcnt vmcnt(6)
	ds_write_b128 v9, v[26:29]
	s_waitcnt vmcnt(5)
	ds_write_b128 v10, v[30:33]
	s_waitcnt vmcnt(4)
	ds_write_b128 v11, v[34:37]
	s_waitcnt vmcnt(3)
	ds_write_b128 v12, v[38:41]
	s_waitcnt vmcnt(2)
	ds_write_b128 v13, v[42:45]
	s_waitcnt vmcnt(1)
	ds_write_b128 v14, v[46:49]
	s_waitcnt vmcnt(0)
	ds_write_b128 v15, v[50:53]
	s_waitcnt lgkmcnt(0)
	s_barrier
	ds_read2st64_b32 v[22:23], v7 offset1:4
	ds_read2st64_b32 v[24:25], v7 offset0:8 offset1:12
	ds_read2st64_b32 v[26:27], v7 offset0:16 offset1:20
	ds_read2st64_b32 v[28:29], v7 offset0:24 offset1:28
	ds_read2st64_b32 v[30:31], v17 offset1:4
	ds_read2st64_b32 v[32:33], v17 offset0:8 offset1:12
	ds_read2st64_b32 v[34:35], v17 offset0:16 offset1:20
	ds_read2st64_b32 v[36:37], v17 offset0:24 offset1:28
	ds_read2st64_b32 v[38:39], v19 offset1:4
	ds_read2st64_b32 v[40:41], v19 offset0:8 offset1:12
	ds_read2st64_b32 v[42:43], v19 offset0:16 offset1:20
	ds_read2st64_b32 v[44:45], v19 offset0:24 offset1:28
	ds_read2st64_b32 v[46:47], v21 offset1:4
	ds_read2st64_b32 v[48:49], v21 offset0:8 offset1:12
	ds_read2st64_b32 v[50:51], v21 offset0:16 offset1:20
	ds_read2st64_b32 v[52:53], v21 offset0:24 offset1:28
	s_waitcnt lgkmcnt(14)
	v_cvt_pk_bf16_f32 v22, v22, v23
	v_cvt_pk_bf16_f32 v23, v24, v25
	s_waitcnt lgkmcnt(13)
	v_cvt_pk_bf16_f32 v24, v26, v27
	s_waitcnt lgkmcnt(12)
	v_cvt_pk_bf16_f32 v25, v28, v29
	s_waitcnt lgkmcnt(11)
	v_cvt_pk_bf16_f32 v26, v30, v31
	s_waitcnt lgkmcnt(10)
	v_cvt_pk_bf16_f32 v27, v32, v33
	s_waitcnt lgkmcnt(9)
	v_cvt_pk_bf16_f32 v28, v34, v35
	s_waitcnt lgkmcnt(8)
	v_cvt_pk_bf16_f32 v29, v36, v37
	s_waitcnt lgkmcnt(7)
	v_cvt_pk_bf16_f32 v30, v38, v39
	s_waitcnt lgkmcnt(6)
	v_cvt_pk_bf16_f32 v31, v40, v41
	s_waitcnt lgkmcnt(5)
	v_cvt_pk_bf16_f32 v32, v42, v43
	s_waitcnt lgkmcnt(4)
	v_cvt_pk_bf16_f32 v33, v44, v45
	s_waitcnt lgkmcnt(3)
	v_cvt_pk_bf16_f32 v34, v46, v47
	s_waitcnt lgkmcnt(2)
	v_cvt_pk_bf16_f32 v35, v48, v49
	s_waitcnt lgkmcnt(1)
	v_cvt_pk_bf16_f32 v36, v50, v51
	s_waitcnt lgkmcnt(0)
	v_cvt_pk_bf16_f32 v37, v52, v53
	global_store_dwordx4 v[54:55], v[22:25], off
	global_store_dwordx4 v[56:57], v[26:29], off
	global_store_dwordx4 v[58:59], v[30:33], off
	global_store_dwordx4 v[60:61], v[34:37], off
	s_barrier
	s_cbranch_scc1 .LBB0_36

; __device__ __forceinline__ unsigned cvt_pk_bf16(float lo, float hi) { unsigned r; asm("v_cvt_pk_bf16_f32 %0, %1, %2" : "=v"(r) : "v"(lo), "v"(hi)); return r; }
; template <bool PERMW, bool PERM32>
; __device__ __forceinline__ void transpose_cvt(const float* __restrict__ src, bf16_t* __restrict__ dst, int K, int N, float* T, int& tile_ctr, int blk, int nblk) {
;     ...
;     for (int tl = tl0; tl < ntiles; tl += nblk) {
;         const int k0 = (tl % nkt) * 64, n0 = (tl / nkt) * 256;
;         { const int n4 = (tid & 63) * 4, sc = PERMW ? win_src_col(n0 + n4) : n0 + n4; f32x4 v[8];
; #pragma unroll
;           for (int i = 0; i < 8; ++i) { const int k = (tid >> 6) + 8 * i; v[i] = *(const f32x4*)(src + (size_t)(k0 + k) * N + sc); }
; #pragma unroll
;           for (int i = 0; i < 8; ++i) { const int k = (tid >> 6) + 8 * i; *(f32x4*)(T + k * 256 + (n4 ^ (((k >> 3) & 7) << 2))) = v[i]; } }
;         __syncthreads();
; #pragma unroll
;         for (int i = 0; i < 4; ++i) { const int pi = tid + 512 * i, q = pi & 7, nl = pi >> 3, x = PERM32 ? (nl & ~31) + perm32(nl & 31) : nl; const float* tp = T + (8 * q) * 256 + (x ^ (q << 2)); uint4 o;
;             o.x = cvt_pk_bf16(tp[0], tp[256]); o.y = cvt_pk_bf16(tp[512], tp[768]); o.z = cvt_pk_bf16(tp[1024], tp[1280]); o.w = cvt_pk_bf16(tp[1536], tp[1792]);
;             *(uint4*)(dst + (size_t)(n0 + nl) * K + k0 + 8 * q) = o; }
;         __syncthreads();
;     }
; __global__ __launch_bounds__(512, 2) void fwd_megakernel(Params p) {
;     ...
;         for (int j = 0; j < nslot; ++j) { int ctr = 0;
;           transpose_cvt<true, true>(p.w_in, WinT, DM, DIN, (float*)shm, ctr, slot0 + j, nslots);
;           transpose_cvt<false, true>(p.w_out, WoutT, DM, DM, (float*)shm, ctr, slot0 + j, nslots);
;           transpose_cvt<false, true>(p.w_ff2, Wff2T, DFF, DM, (float*)shm, ctr, slot0 + j, nslots);
;           transpose_cvt<false, true>(p.w_ff1, Wff1T, DM, DFF, (float*)shm, ctr, slot0 + j, nslots); } }
.LBB0_39:
	s_ashr_i32 s14, s68, 31
	s_lshr_b32 s14, s14, 28
	s_add_i32 s14, s68, s14
	s_ashr_i32 s14, s14, 4
	s_lshl_b32 s71, s14, 10
	s_lshl_b32 s15, s14, 8
	s_sub_i32 s14, s69, s71
	v_add_u32_e32 v24, s14, v6
	v_or_b32_e32 v22, s15, v1
	v_add_u32_e32 v26, 8, v24
	v_add_u32_e32 v28, 16, v24
	v_add_u32_e32 v30, 24, v24
	v_add_u32_e32 v32, 32, v24
	v_add_u32_e32 v34, 40, v24
	v_add_u32_e32 v36, 48, v24
	v_add_u32_e32 v38, 56, v24
	v_ashrrev_i32_e32 v23, 31, v22
	v_ashrrev_i32_e32 v25, 31, v24
	v_ashrrev_i32_e32 v27, 31, v26
	v_ashrrev_i32_e32 v29, 31, v28
	v_ashrrev_i32_e32 v31, 31, v30
	v_ashrrev_i32_e32 v33, 31, v32
	v_ashrrev_i32_e32 v35, 31, v34
	v_ashrrev_i32_e32 v37, 31, v36
	v_ashrrev_i32_e32 v39, 31, v38
	v_lshl_add_u64 v[22:23], v[22:23], 2, s[30:31]
	v_lshlrev_b64 v[24:25], 14, v[24:25]
	v_lshlrev_b64 v[26:27], 14, v[26:27]
	v_lshlrev_b64 v[28:29], 14, v[28:29]
	v_lshlrev_b64 v[30:31], 14, v[30:31]
	v_lshlrev_b64 v[32:33], 14, v[32:33]
	v_lshlrev_b64 v[34:35], 14, v[34:35]
	v_lshlrev_b64 v[36:37], 14, v[36:37]
	v_lshlrev_b64 v[38:39], 14, v[38:39]
	v_lshl_add_u64 v[24:25], v[22:23], 0, v[24:25]
	v_lshl_add_u64 v[26:27], v[22:23], 0, v[26:27]
	v_lshl_add_u64 v[40:41], v[22:23], 0, v[28:29]
	v_lshl_add_u64 v[42:43], v[22:23], 0, v[30:31]
	v_lshl_add_u64 v[44:45], v[22:23], 0, v[32:33]
	v_lshl_add_u64 v[46:47], v[22:23], 0, v[34:35]
	v_lshl_add_u64 v[48:49], v[22:23], 0, v[36:37]
	v_lshl_add_u64 v[50:51], v[22:23], 0, v[38:39]
	global_load_dwordx4 v[22:25], v[24:25], off nt
	s_nop 0
	global_load_dwordx4 v[26:29], v[26:27], off nt
	s_nop 0
	global_load_dwordx4 v[30:33], v[40:41], off nt
	global_load_dwordx4 v[34:37], v[42:43], off nt
	s_nop 0
	global_load_dwordx4 v[38:41], v[44:45], off nt
	s_nop 0
	global_load_dwordx4 v[42:45], v[46:47], off nt
	s_nop 0
	global_load_dwordx4 v[46:49], v[48:49], off nt
	s_nop 0
	global_load_dwordx4 v[50:53], v[50:51], off nt
	v_add_u32_e32 v54, s15, v2
	v_add_u32_e32 v56, s15, v16
	v_add_u32_e32 v58, s15, v18
	v_add_u32_e32 v60, s15, v20
	s_ashr_i32 s15, s14, 31
	v_ashrrev_i32_e32 v55, 31, v54
	s_add_i32 s68, s68, s33
	s_add_i32 s69, s69, s70
	v_ashrrev_i32_e32 v57, 31, v56
	v_ashrrev_i32_e32 v59, 31, v58
	v_ashrrev_i32_e32 v61, 31, v60
	v_lshl_add_u64 v[62:63], s[14:15], 1, v[4:5]
	v_lshlrev_b64 v[54:55], 11, v[54:55]
	v_lshlrev_b64 v[56:57], 11, v[56:57]
	v_lshlrev_b64 v[58:59], 11, v[58:59]
	v_lshlrev_b64 v[60:61], 11, v[60:61]
	s_cmpk_lt_i32 s68, 0x100
	v_lshl_add_u64 v[54:55], v[62:63], 0, v[54:55]
	v_lshl_add_u64 v[56:57], v[62:63], 0, v[56:57]
	v_lshl_add_u64 v[58:59], v[62:63], 0, v[58:59]
	v_lshl_add_u64 v[60:61], v[62:63], 0, v[60:61]
	s_waitcnt vmcnt(7)
	ds_write_b128 v8, v[22:25]
	s_waitcnt vmcnt(6)
	ds_write_b128 v9, v[26:29]
	s_waitcnt vmcnt(5)
	ds_write_b128 v10, v[30:33]
	s_waitcnt vmcnt(4)
	ds_write_b128 v11, v[34:37]
	s_waitcnt vmcnt(3)
	ds_write_b128 v12, v[38:41]
	s_waitcnt vmcnt(2)
	ds_write_b128 v13, v[42:45]
	s_waitcnt vmcnt(1)
	ds_write_b128 v14, v[46:49]
	s_waitcnt vmcnt(0)
	ds_write_b128 v15, v[50:53]
	s_waitcnt lgkmcnt(0)
	s_barrier
	ds_read2st64_b32 v[22:23], v7 offset1:4
	ds_read2st64_b32 v[24:25], v7 offset0:8 offset1:12
	ds_read2st64_b32 v[26:27], v7 offset0:16 offset1:20
	ds_read2st64_b32 v[28:29], v7 offset0:24 offset1:28
	ds_read2st64_b32 v[30:31], v17 offset1:4
	ds_read2st64_b32 v[32:33], v17 offset0:8 offset1:12
	ds_read2st64_b32 v[34:35], v17 offset0:16 offset1:20
	ds_read2st64_b32 v[36:37], v17 offset0:24 offset1:28
	ds_read2st64_b32 v[38:39], v19 offset1:4
	ds_read2st64_b32 v[40:41], v19 offset0:8 offset1:12
	ds_read2st64_b32 v[42:43], v19 offset0:16 offset1:20
	ds_read2st64_b32 v[44:45], v19 offset0:24 offset1:28
	ds_read2st64_b32 v[46:47], v21 offset1:4
	ds_read2st64_b32 v[48:49], v21 offset0:8 offset1:12
	ds_read2st64_b32 v[50:51], v21 offset0:16 offset1:20
	ds_read2st64_b32 v[52:53], v21 offset0:24 offset1:28
	s_waitcnt lgkmcnt(14)
	v_cvt_pk_bf16_f32 v22, v22, v23
	v_cvt_pk_bf16_f32 v23, v24, v25
	s_waitcnt lgkmcnt(13)
	v_cvt_pk_bf16_f32 v24, v26, v27
	s_waitcnt lgkmcnt(12)
	v_cvt_pk_bf16_f32 v25, v28, v29
	s_waitcnt lgkmcnt(11)
	v_cvt_pk_bf16_f32 v26, v30, v31
	s_waitcnt lgkmcnt(10)
	v_cvt_pk_bf16_f32 v27, v32, v33
	s_waitcnt lgkmcnt(9)
	v_cvt_pk_bf16_f32 v28, v34, v35
	s_waitcnt lgkmcnt(8)
	v_cvt_pk_bf16_f32 v29, v36, v37
	s_waitcnt lgkmcnt(7)
	v_cvt_pk_bf16_f32 v30, v38, v39
	s_waitcnt lgkmcnt(6)
	v_cvt_pk_bf16_f32 v31, v40, v41
	s_waitcnt lgkmcnt(5)
	v_cvt_pk_bf16_f32 v32, v42, v43
	s_waitcnt lgkmcnt(4)
	v_cvt_pk_bf16_f32 v33, v44, v45
	s_waitcnt lgkmcnt(3)
	v_cvt_pk_bf16_f32 v34, v46, v47
	s_waitcnt lgkmcnt(2)
	v_cvt_pk_bf16_f32 v35, v48, v49
	s_waitcnt lgkmcnt(1)
	v_cvt_pk_bf16_f32 v36, v50, v51
	s_waitcnt lgkmcnt(0)
	v_cvt_pk_bf16_f32 v37, v52, v53
	global_store_dwordx4 v[54:55], v[22:25], off
	global_store_dwordx4 v[56:57], v[26:29], off
	global_store_dwordx4 v[58:59], v[30:33], off
	global_store_dwordx4 v[60:61], v[34:37], off
	s_barrier
	s_cbranch_scc1 .LBB0_39
	s_branch .LBB0_21

; __device__ __forceinline__ unsigned cvt_pk_bf16(float lo, float hi) { unsigned r; asm("v_cvt_pk_bf16_f32 %0, %1, %2" : "=v"(r) : "v"(lo), "v"(hi)); return r; }
; __device__ __forceinline__ void mod_phase(const Params& p, const bf16_t* __restrict__ Sb, float* smem) {
;     ...
;         for (int kk = 0; kk < 4; ++kk) { const float* wp = p.w_ada + (size_t)(w * 128 + kk * 32 + fq * 8) * NMOD + col0 + 2 * fr;
; #pragma unroll
;             for (int i = 0; i < 4; ++i) { const float2 v0 = *(const float2*)(wp + (size_t)(2 * i) * NMOD), v1 = *(const float2*)(wp + (size_t)(2 * i + 1) * NMOD);
;                 wfA[kk].u[i] = cvt_pk_bf16(v0.x, v1.x); wfB[kk].u[i] = cvt_pk_bf16(v0.y, v1.y); } }
; #pragma unroll
;         for (int kk = 0; kk < 4; ++kk) {
; #pragma unroll
;             for (int bt = 0; bt < 9; ++bt) { Frag sf; sf.q = *(const uint4*)(Sb + (size_t)(bt * 16 + fr) * DM + w * 128 + kk * 32 + fq * 8);
;                 acc[0][bt] = __builtin_amdgcn_mfma_f32_16x16x32_bf16(wfA[kk].v, sf.v, acc[0][bt], 0, 0, 0);
;                 acc[1][bt] = __builtin_amdgcn_mfma_f32_16x16x32_bf16(wfB[kk].v, sf.v, acc[1][bt], 0, 0, 0); } }
.LBB0_70:
	s_lshl_b32 s10, s53, 5
	s_ashr_i32 s11, s10, 31
	v_lshl_add_u64 v[0:1], s[10:11], 2, v[138:139]
	v_lshl_add_u64 v[10:11], v[0:1], 0, v[142:143]
	v_add_co_u32_e32 v2, vcc, 0x6000, v10
	s_nop 1
	v_addc_co_u32_e32 v3, vcc, 0, v11, vcc
	v_add_co_u32_e32 v6, vcc, 0xc000, v10
	s_nop 1
	v_addc_co_u32_e32 v7, vcc, 0, v11, vcc
	v_add_co_u32_e32 v12, vcc, 0x12000, v10
	s_nop 1
	v_addc_co_u32_e32 v13, vcc, 0, v11, vcc
	global_load_dwordx2 v[4:5], v[10:11], off nt
	global_load_dwordx2 v[8:9], v[2:3], off nt
	s_nop 0
	global_load_dwordx2 v[2:3], v[6:7], off nt
	s_nop 0
	global_load_dwordx2 v[6:7], v[12:13], off nt
	v_add_co_u32_e32 v12, vcc, s13, v10
	s_waitcnt vmcnt(2)
	v_cvt_pk_bf16_f32 v30, v4, v8
	s_nop 0
	v_addc_co_u32_e32 v13, vcc, 0, v11, vcc
	v_add_co_u32_e32 v14, vcc, 0x1e000, v10
	v_cvt_pk_bf16_f32 v4, v5, v9
	s_waitcnt vmcnt(0)
	v_cvt_pk_bf16_f32 v31, v2, v6
	v_cvt_pk_bf16_f32 v5, v3, v7
	v_lshl_add_u64 v[2:3], v[0:1], 0, v[144:145]
	v_addc_co_u32_e32 v15, vcc, 0, v11, vcc
	v_add_co_u32_e32 v16, vcc, 0x24000, v10
	s_nop 1
	v_addc_co_u32_e32 v17, vcc, 0, v11, vcc
	v_add_co_u32_e32 v18, vcc, 0x2a000, v10
	s_nop 1
	v_addc_co_u32_e32 v19, vcc, 0, v11, vcc
	global_load_dwordx2 v[10:11], v[12:13], off nt
	s_nop 0
	global_load_dwordx2 v[12:13], v[14:15], off nt
	s_nop 0
	global_load_dwordx2 v[14:15], v[16:17], off nt
	s_nop 0
	global_load_dwordx2 v[16:17], v[18:19], off nt
	s_nop 0
	global_load_dwordx4 v[18:21], v[72:73], off
	global_load_dwordx4 v[22:25], v[74:75], off
	global_load_dwordx4 v[26:29], v[72:73], off offset:64
	s_waitcnt vmcnt(5)
	v_cvt_pk_bf16_f32 v32, v10, v12
	s_waitcnt vmcnt(3)
	v_cvt_pk_bf16_f32 v33, v14, v16
	s_waitcnt vmcnt(2)
	v_mfma_f32_16x16x32_bf16 v[34:37], v[30:33], v[18:21], 0
	v_cvt_pk_bf16_f32 v6, v11, v13
	v_cvt_pk_bf16_f32 v7, v15, v17
	global_load_dwordx4 v[12:15], v[76:77], off
	global_load_dwordx4 v[42:45], v[78:79], off
	v_mfma_f32_16x16x32_bf16 v[8:11], v[4:7], v[18:21], 0
	global_load_dwordx4 v[46:49], v[80:81], off
	global_load_dwordx4 v[58:61], v[82:83], off
	global_load_dwordx4 v[62:65], v[84:85], off
	global_load_dwordx4 v[172:175], v[118:119], off
	s_waitcnt vmcnt(7)
	v_mfma_f32_16x16x32_bf16 v[16:19], v[30:33], v[22:25], 0
	global_load_dwordx4 v[180:183], v[120:121], off
	v_mfma_f32_16x16x32_bf16 v[20:23], v[4:7], v[22:25], 0
	v_add_co_u32_e32 v24, vcc, s12, v2
	s_mov_b64 s[8:9], vcc
	v_add_co_u32_e32 v70, vcc, s30, v2
	v_addc_co_u32_e64 v25, s[8:9], 0, v3, s[8:9]
	s_nop 0
	v_addc_co_u32_e32 v71, vcc, 0, v3, vcc
	v_add_co_u32_e32 v188, vcc, s31, v2
	s_waitcnt vmcnt(6)
	v_mfma_f32_16x16x32_bf16 v[38:41], v[30:33], v[12:15], 0
	v_addc_co_u32_e32 v189, vcc, 0, v3, vcc
	v_add_co_u32_e32 v190, vcc, s13, v2
	v_mfma_f32_16x16x32_bf16 v[12:15], v[4:7], v[12:15], 0
	s_nop 0
	v_addc_co_u32_e32 v191, vcc, 0, v3, vcc
	v_add_co_u32_e32 v192, vcc, s33, v2
	s_waitcnt vmcnt(5)
	v_mfma_f32_16x16x32_bf16 v[50:53], v[30:33], v[42:45], 0
	v_addc_co_u32_e32 v193, vcc, 0, v3, vcc
	v_add_co_u32_e32 v194, vcc, s48, v2
	v_mfma_f32_16x16x32_bf16 v[42:45], v[4:7], v[42:45], 0
	s_nop 0
	v_addc_co_u32_e32 v195, vcc, 0, v3, vcc
	v_add_co_u32_e32 v196, vcc, s49, v2
	s_waitcnt vmcnt(4)
	v_mfma_f32_16x16x32_bf16 v[54:57], v[30:33], v[46:49], 0
	v_addc_co_u32_e32 v197, vcc, 0, v3, vcc
	global_load_dwordx2 v[198:199], v[2:3], off nt
	s_nop 0
	global_load_dwordx2 v[24:25], v[24:25], off nt
	s_nop 0
	global_load_dwordx2 v[70:71], v[70:71], off nt
	s_nop 0
	global_load_dwordx2 v[200:201], v[188:189], off nt
	s_nop 0
	global_load_dwordx2 v[190:191], v[190:191], off nt
	s_nop 0
	global_load_dwordx2 v[202:203], v[192:193], off nt
	global_load_dwordx2 v[204:205], v[194:195], off nt
	s_nop 0
	global_load_dwordx2 v[196:197], v[196:197], off nt
	v_mfma_f32_16x16x32_bf16 v[46:49], v[4:7], v[46:49], 0
	global_load_dwordx4 v[192:195], v[86:87], off
	s_waitcnt vmcnt(7)
	v_cvt_pk_bf16_f32 v188, v199, v25
	v_mfma_f32_16x16x32_bf16 v[66:69], v[30:33], v[58:61], 0
	s_waitcnt vmcnt(5)
	v_cvt_pk_bf16_f32 v189, v71, v201
	v_mfma_f32_16x16x32_bf16 v[58:61], v[4:7], v[58:61], 0
	v_mfma_f32_16x16x32_bf16 v[176:179], v[30:33], v[62:65], 0
	v_mfma_f32_16x16x32_bf16 v[62:65], v[4:7], v[62:65], 0
	v_mfma_f32_16x16x32_bf16 v[184:187], v[30:33], v[172:175], 0
	v_mfma_f32_16x16x32_bf16 v[172:175], v[4:7], v[172:175], 0
	v_mfma_f32_16x16x32_bf16 v[30:33], v[30:33], v[180:183], 0
	v_mfma_f32_16x16x32_bf16 v[2:5], v[4:7], v[180:183], 0
	v_cvt_pk_bf16_f32 v180, v198, v24
	v_cvt_pk_bf16_f32 v181, v70, v200
	s_waitcnt vmcnt(3)
	v_cvt_pk_bf16_f32 v182, v190, v202
	s_waitcnt vmcnt(1)
	v_cvt_pk_bf16_f32 v183, v204, v196
	v_cvt_pk_bf16_f32 v190, v191, v203
	v_cvt_pk_bf16_f32 v191, v205, v197
	s_nop 0
	v_mfma_f32_16x16x32_bf16 v[34:37], v[180:183], v[26:29], v[34:37]
	v_mfma_f32_16x16x32_bf16 v[6:9], v[188:191], v[26:29], v[8:11]
	global_load_dwordx4 v[24:27], v[88:89], off
	s_waitcnt vmcnt(1)
	v_mfma_f32_16x16x32_bf16 v[16:19], v[180:183], v[192:195], v[16:19]
	v_mfma_f32_16x16x32_bf16 v[20:23], v[188:191], v[192:195], v[20:23]
	global_load_dwordx4 v[192:195], v[90:91], off
	s_waitcnt vmcnt(1)
	v_mfma_f32_16x16x32_bf16 v[38:41], v[180:183], v[24:27], v[38:41]
	v_mfma_f32_16x16x32_bf16 v[10:13], v[188:191], v[24:27], v[12:15]
	global_load_dwordx4 v[24:27], v[92:93], off
	s_waitcnt vmcnt(1)
	v_mfma_f32_16x16x32_bf16 v[50:53], v[180:183], v[192:195], v[50:53]
	v_lshl_add_u64 v[14:15], v[0:1], 0, v[146:147]
	v_add_co_u32_e32 v28, vcc, s12, v14
	v_mfma_f32_16x16x32_bf16 v[42:45], v[188:191], v[192:195], v[42:45]
	global_load_dwordx4 v[192:195], v[94:95], off
	v_addc_co_u32_e32 v29, vcc, 0, v15, vcc
	s_waitcnt vmcnt(1)
; __device__ __forceinline__ unsigned cvt_pk_bf16(float lo, float hi) { unsigned r; asm("v_cvt_pk_bf16_f32 %0, %1, %2" : "=v"(r) : "v"(lo), "v"(hi)); return r; }
; __device__ __forceinline__ void mod_phase(const Params& p, const bf16_t* __restrict__ Sb, float* smem) {
;     ...
;         for (int kk = 0; kk < 4; ++kk) { const float* wp = p.w_ada + (size_t)(w * 128 + kk * 32 + fq * 8) * NMOD + col0 + 2 * fr;
; #pragma unroll
;             for (int i = 0; i < 4; ++i) { const float2 v0 = *(const float2*)(wp + (size_t)(2 * i) * NMOD), v1 = *(const float2*)(wp + (size_t)(2 * i + 1) * NMOD);
;                 wfA[kk].u[i] = cvt_pk_bf16(v0.x, v1.x); wfB[kk].u[i] = cvt_pk_bf16(v0.y, v1.y); } }
; #pragma unroll
;         for (int kk = 0; kk < 4; ++kk) {
; #pragma unroll
;             for (int bt = 0; bt < 9; ++bt) { Frag sf; sf.q = *(const uint4*)(Sb + (size_t)(bt * 16 + fr) * DM + w * 128 + kk * 32 + fq * 8);
;                 acc[0][bt] = __builtin_amdgcn_mfma_f32_16x16x32_bf16(wfA[kk].v, sf.v, acc[0][bt], 0, 0, 0);
;                 acc[1][bt] = __builtin_amdgcn_mfma_f32_16x16x32_bf16(wfB[kk].v, sf.v, acc[1][bt], 0, 0, 0); } }
	v_mfma_f32_16x16x32_bf16 v[54:57], v[180:183], v[24:27], v[54:57]
	v_add_co_u32_e32 v70, vcc, s30, v14
	v_lshl_add_u64 v[0:1], v[0:1], 0, v[148:149]
	v_mfma_f32_16x16x32_bf16 v[24:27], v[188:191], v[24:27], v[46:49]
	v_addc_co_u32_e32 v71, vcc, 0, v15, vcc
	s_nop 1
	global_load_dwordx4 v[46:49], v[96:97], off
	s_waitcnt vmcnt(1)
	v_mfma_f32_16x16x32_bf16 v[66:69], v[180:183], v[192:195], v[66:69]
	v_mfma_f32_16x16x32_bf16 v[58:61], v[188:191], v[192:195], v[58:61]
	global_load_dwordx4 v[192:195], v[98:99], off
	s_waitcnt vmcnt(1)
	v_mfma_f32_16x16x32_bf16 v[176:179], v[180:183], v[46:49], v[176:179]
	v_mfma_f32_16x16x32_bf16 v[46:49], v[188:191], v[46:49], v[62:65]
	s_nop 2
	global_load_dwordx4 v[62:65], v[100:101], off
	s_waitcnt vmcnt(1)
	v_mfma_f32_16x16x32_bf16 v[184:187], v[180:183], v[192:195], v[184:187]
	v_mfma_f32_16x16x32_bf16 v[172:175], v[188:191], v[192:195], v[172:175]
	v_add_co_u32_e32 v192, vcc, s31, v14
	s_nop 1
	v_addc_co_u32_e32 v193, vcc, 0, v15, vcc
	v_add_co_u32_e32 v194, vcc, s13, v14
	s_waitcnt vmcnt(0)
	v_mfma_f32_16x16x32_bf16 v[2:5], v[188:191], v[62:65], v[2:5]
	v_addc_co_u32_e32 v195, vcc, 0, v15, vcc
	v_add_co_u32_e32 v196, vcc, s33, v14
	s_nop 1
	v_addc_co_u32_e32 v197, vcc, 0, v15, vcc
	v_add_co_u32_e32 v198, vcc, s48, v14
	s_nop 1
	v_addc_co_u32_e32 v199, vcc, 0, v15, vcc
	v_add_co_u32_e32 v200, vcc, s49, v14
	s_nop 1
	v_addc_co_u32_e32 v201, vcc, 0, v15, vcc
	global_load_dwordx2 v[14:15], v[14:15], off nt
	s_nop 0
	global_load_dwordx2 v[202:203], v[28:29], off nt
	s_nop 0
	global_load_dwordx2 v[70:71], v[70:71], off nt
	s_nop 0
	global_load_dwordx2 v[204:205], v[192:193], off nt
	global_load_dwordx2 v[206:207], v[194:195], off nt
	global_load_dwordx2 v[208:209], v[196:197], off nt
	global_load_dwordx2 v[210:211], v[198:199], off nt
	s_nop 0
	global_load_dwordx2 v[200:201], v[200:201], off nt
	v_mfma_f32_16x16x32_bf16 v[28:31], v[180:183], v[62:65], v[30:33]
	global_load_dwordx4 v[180:183], v[72:73], off offset:128
	global_load_dwordx4 v[192:195], v[72:73], off offset:192
	s_waitcnt vmcnt(8)
	v_cvt_pk_bf16_f32 v62, v14, v202
	v_cvt_pk_bf16_f32 v32, v15, v203
	s_waitcnt vmcnt(6)
	v_cvt_pk_bf16_f32 v63, v70, v204
	s_waitcnt vmcnt(4)
	v_cvt_pk_bf16_f32 v64, v206, v208
	global_load_dwordx4 v[188:191], v[102:103], off
	s_waitcnt vmcnt(3)
	v_cvt_pk_bf16_f32 v65, v210, v200
	v_cvt_pk_bf16_f32 v33, v71, v205
	s_waitcnt vmcnt(2)
	v_mfma_f32_16x16x32_bf16 v[196:199], v[62:65], v[180:183], v[34:37]
	v_cvt_pk_bf16_f32 v34, v207, v209
	v_cvt_pk_bf16_f32 v35, v211, v201
	s_nop 0
	v_mfma_f32_16x16x32_bf16 v[6:9], v[32:35], v[180:183], v[6:9]
	global_load_dwordx4 v[180:183], v[104:105], off
	s_waitcnt vmcnt(1)
	v_mfma_f32_16x16x32_bf16 v[14:17], v[62:65], v[188:191], v[16:19]
	s_nop 2
	v_add_co_u32_e32 v18, vcc, s12, v0
	v_mfma_f32_16x16x32_bf16 v[20:23], v[32:35], v[188:191], v[20:23]
	global_load_dwordx4 v[188:191], v[106:107], off
	v_addc_co_u32_e32 v19, vcc, 0, v1, vcc
	s_waitcnt vmcnt(1)
	v_mfma_f32_16x16x32_bf16 v[36:39], v[62:65], v[180:183], v[38:41]
	v_mfma_f32_16x16x32_bf16 v[180:183], v[32:35], v[180:183], v[10:13]
	s_nop 2
	global_load_dwordx4 v[10:13], v[108:109], off
	s_waitcnt vmcnt(1)
	v_mfma_f32_16x16x32_bf16 v[50:53], v[62:65], v[188:191], v[50:53]
	v_mfma_f32_16x16x32_bf16 v[40:43], v[32:35], v[188:191], v[42:45]
	global_load_dwordx4 v[188:191], v[110:111], off
	s_waitcnt vmcnt(1)
	v_mfma_f32_16x16x32_bf16 v[54:57], v[62:65], v[10:13], v[54:57]
	v_mfma_f32_16x16x32_bf16 v[200:203], v[32:35], v[10:13], v[24:27]
	global_load_dwordx4 v[10:13], v[112:113], off
	s_nop 1
	global_load_dwordx4 v[24:27], v[114:115], off
	s_waitcnt vmcnt(2)
	v_mfma_f32_16x16x32_bf16 v[66:69], v[62:65], v[188:191], v[66:69]
	v_mfma_f32_16x16x32_bf16 v[58:61], v[32:35], v[188:191], v[58:61]
	s_waitcnt vmcnt(1)
	v_mfma_f32_16x16x32_bf16 v[176:179], v[62:65], v[10:13], v[176:179]
	v_mfma_f32_16x16x32_bf16 v[188:191], v[32:35], v[10:13], v[46:49]
	global_load_dwordx4 v[10:13], v[116:117], off
	s_waitcnt vmcnt(1)
; __device__ __forceinline__ unsigned cvt_pk_bf16(float lo, float hi) { unsigned r; asm("v_cvt_pk_bf16_f32 %0, %1, %2" : "=v"(r) : "v"(lo), "v"(hi)); return r; }
; __device__ __forceinline__ void mod_phase(const Params& p, const bf16_t* __restrict__ Sb, float* smem) {
;     ...
;         for (int kk = 0; kk < 4; ++kk) { const float* wp = p.w_ada + (size_t)(w * 128 + kk * 32 + fq * 8) * NMOD + col0 + 2 * fr;
; #pragma unroll
;             for (int i = 0; i < 4; ++i) { const float2 v0 = *(const float2*)(wp + (size_t)(2 * i) * NMOD), v1 = *(const float2*)(wp + (size_t)(2 * i + 1) * NMOD);
;                 wfA[kk].u[i] = cvt_pk_bf16(v0.x, v1.x); wfB[kk].u[i] = cvt_pk_bf16(v0.y, v1.y); } }
; #pragma unroll
;         for (int kk = 0; kk < 4; ++kk) {
; #pragma unroll
;             for (int bt = 0; bt < 9; ++bt) { Frag sf; sf.q = *(const uint4*)(Sb + (size_t)(bt * 16 + fr) * DM + w * 128 + kk * 32 + fq * 8);
;                 acc[0][bt] = __builtin_amdgcn_mfma_f32_16x16x32_bf16(wfA[kk].v, sf.v, acc[0][bt], 0, 0, 0);
;                 acc[1][bt] = __builtin_amdgcn_mfma_f32_16x16x32_bf16(wfB[kk].v, sf.v, acc[1][bt], 0, 0, 0); } }
;         if (w >= 4) {
; #pragma unroll
;             for (int bt = 0; bt < 9; ++bt) { red[((w - 4) * 18 + bt) * 64 + lane] = acc[0][bt]; red[((w - 4) * 18 + 9 + bt) * 64 + lane] = acc[1][bt]; } }
	v_mfma_f32_16x16x32_bf16 v[184:187], v[62:65], v[24:27], v[184:187]
	v_mfma_f32_16x16x32_bf16 v[172:175], v[32:35], v[24:27], v[172:175]
	v_add_co_u32_e32 v24, vcc, s30, v0
	s_nop 1
	v_addc_co_u32_e32 v25, vcc, 0, v1, vcc
	v_add_co_u32_e32 v26, vcc, s31, v0
	s_waitcnt vmcnt(0)
	v_mfma_f32_16x16x32_bf16 v[204:207], v[62:65], v[10:13], v[28:31]
	v_addc_co_u32_e32 v27, vcc, 0, v1, vcc
	s_nop 1
	v_add_co_u32_e32 v28, vcc, s13, v0
	v_mfma_f32_16x16x32_bf16 v[208:211], v[32:35], v[10:13], v[2:5]
	s_nop 0
	v_addc_co_u32_e32 v29, vcc, 0, v1, vcc
	v_add_co_u32_e32 v30, vcc, s33, v0
	s_nop 1
	v_addc_co_u32_e32 v31, vcc, 0, v1, vcc
	v_add_co_u32_e32 v44, vcc, s48, v0
	s_nop 1
	v_addc_co_u32_e32 v45, vcc, 0, v1, vcc
	v_add_co_u32_e32 v46, vcc, s49, v0
	s_nop 1
	v_addc_co_u32_e32 v47, vcc, 0, v1, vcc
	global_load_dwordx2 v[0:1], v[0:1], off nt
	s_nop 0
	global_load_dwordx2 v[18:19], v[18:19], off nt
	s_nop 0
	global_load_dwordx2 v[24:25], v[24:25], off nt
	s_nop 0
	global_load_dwordx2 v[26:27], v[26:27], off nt
	s_nop 0
	global_load_dwordx2 v[28:29], v[28:29], off nt
	s_nop 0
	global_load_dwordx2 v[30:31], v[30:31], off nt
	s_nop 0
	global_load_dwordx2 v[44:45], v[44:45], off nt
	s_nop 0
	global_load_dwordx2 v[46:47], v[46:47], off nt
	s_waitcnt vmcnt(4)
	v_cvt_pk_bf16_f32 v213, v24, v26
	global_load_dwordx4 v[10:13], v[122:123], off
	v_cvt_pk_bf16_f32 v217, v25, v27
	global_load_dwordx4 v[24:27], v[124:125], off
	v_cvt_pk_bf16_f32 v212, v0, v18
	v_cvt_pk_bf16_f32 v216, v1, v19
	s_waitcnt vmcnt(4)
	v_cvt_pk_bf16_f32 v214, v28, v30
	s_waitcnt vmcnt(2)
	v_cvt_pk_bf16_f32 v215, v44, v46
	v_cvt_pk_bf16_f32 v218, v29, v31
	v_cvt_pk_bf16_f32 v219, v45, v47
	global_load_dwordx4 v[28:31], v[126:127], off
	v_mfma_f32_16x16x32_bf16 v[4:7], v[216:219], v[192:195], v[6:9]
	s_waitcnt vmcnt(2)
	v_mfma_f32_16x16x32_bf16 v[16:19], v[212:215], v[10:13], v[14:17]
	v_mfma_f32_16x16x32_bf16 v[8:11], v[216:219], v[10:13], v[20:23]
	s_waitcnt vmcnt(1)
	v_mfma_f32_16x16x32_bf16 v[12:15], v[212:215], v[24:27], v[36:39]
	s_nop 2
	global_load_dwordx4 v[36:39], v[128:129], off
	v_mfma_f32_16x16x32_bf16 v[20:23], v[216:219], v[24:27], v[180:183]
	s_waitcnt vmcnt(1)
	v_mfma_f32_16x16x32_bf16 v[32:35], v[212:215], v[28:31], v[50:53]
	v_mfma_f32_16x16x32_bf16 v[24:27], v[216:219], v[28:31], v[40:43]
	s_waitcnt vmcnt(0)
	v_mfma_f32_16x16x32_bf16 v[28:31], v[212:215], v[36:39], v[54:57]
	s_nop 0
	global_load_dwordx4 v[40:43], v[130:131], off
	s_nop 0
	global_load_dwordx4 v[52:55], v[132:133], off
	s_waitcnt vmcnt(1)
	v_mfma_f32_16x16x32_bf16 v[48:51], v[212:215], v[40:43], v[66:69]
	v_mfma_f32_16x16x32_bf16 v[40:43], v[216:219], v[40:43], v[58:61]
	s_waitcnt vmcnt(0)
	v_mfma_f32_16x16x32_bf16 v[44:47], v[212:215], v[52:55], v[176:179]
	s_nop 0
	global_load_dwordx4 v[56:59], v[134:135], off
	s_nop 0
	global_load_dwordx4 v[176:179], v[136:137], off
	v_mfma_f32_16x16x32_bf16 v[0:3], v[212:215], v[192:195], v[196:199]
	v_mfma_f32_16x16x32_bf16 v[36:39], v[216:219], v[36:39], v[200:203]
	v_mfma_f32_16x16x32_bf16 v[52:55], v[216:219], v[52:55], v[188:191]
	s_waitcnt vmcnt(1)
	v_mfma_f32_16x16x32_bf16 v[68:71], v[212:215], v[56:59], v[184:187]
	v_mfma_f32_16x16x32_bf16 v[60:63], v[216:219], v[56:59], v[172:175]
	s_waitcnt vmcnt(0)
	v_mfma_f32_16x16x32_bf16 v[64:67], v[212:215], v[176:179], v[204:207]
	v_mfma_f32_16x16x32_bf16 v[56:59], v[216:219], v[176:179], v[208:211]
	s_and_saveexec_b64 s[8:9], s[0:1]
	s_cbranch_execz .LBB0_72
	ds_write_b128 v151, v[0:3]
	ds_write_b128 v153, v[4:7]
	ds_write_b128 v154, v[16:19]
	ds_write_b128 v155, v[8:11]
	ds_write_b128 v156, v[12:15]
	ds_write_b128 v157, v[20:23]
	ds_write_b128 v158, v[32:35]
	ds_write_b128 v159, v[24:27]
	ds_write_b128 v160, v[28:31]
	ds_write_b128 v161, v[36:39]
	ds_write_b128 v162, v[48:51]
	ds_write_b128 v163, v[40:43]
	ds_write_b128 v164, v[44:47]
	ds_write_b128 v165, v[52:55]
	ds_write_b128 v166, v[68:71]
	ds_write_b128 v167, v[60:63]
	ds_write_b128 v168, v[64:67]
	ds_write_b128 v169, v[56:59]

; __device__ __forceinline__ int fresh_tid() { int t = threadIdx.x; asm volatile("" : "+v"(t)); return t; }
; __device__ __forceinline__ void p1_prompt_rows(const Params& p) {
;     const int tid = fresh_tid(), lane = tid & 63, gw = blockIdx.x * 8 + (tid >> 6);
;     const float* mb = (const float*)(p.ws + WS_MOD) + (size_t)(gw >> 8) * NMOD; bf16_t* H = (bf16_t*)(p.ws + WS_H);
;     f32x4 gs[4], sh[4];
; #pragma unroll
;     for (int i = 0; i < 4; ++i) { const int c = (i >> 1) * 512 + lane * 8 + (i & 1) * 4; gs[i] = *(const f32x4*)(p.g_mix + c) * (*(const f32x4*)(mb + 1024 + c) + 1.f); sh[i] = *(const f32x4*)(mb + c); }
; #pragma unroll
;     for (int trip = 0; trip < 2; ++trip) { const int rowb = gw * 8 + trip * 4;
;         f32x4 v[4][4];
; #pragma unroll
;         for (int q = 0; q < 4; ++q)
; #pragma unroll
;             for (int i = 0; i < 4; ++i) v[q][i] = *(const f32x4*)(p.x_prompt + (size_t)(rowb + q) * DM + (i >> 1) * 512 + lane * 8 + (i & 1) * 4);
;         __builtin_amdgcn_sched_barrier(0);
; #pragma unroll
;         for (int q = 0; q < 4; ++q) { float ss = 0.f;
; #pragma unroll
;             for (int i = 0; i < 4; ++i) ss += v[q][i][0] * v[q][i][0] + v[q][i][1] * v[q][i][1] + v[q][i][2] * v[q][i][2] + v[q][i][3] * v[q][i][3];
; #pragma unroll
;             for (int o = 1; o < 64; o <<= 1) ss += __shfl_xor(ss, o);
.LBB0_133:
	s_or_b64 exec, exec, s[0:1]
	s_add_u32 s26, s58, 0x1a70000
	v_mov_b32_e32 v2, v224
	s_addc_u32 s27, s59, 0
	s_waitcnt lgkmcnt(0)
	s_barrier
	s_lshl_b32 s95, s2, 3
	s_mov_b64 s[10:11], 0x1000
	v_ashrrev_i32_e32 v0, 6, v2
	v_add_u32_e32 v20, s95, v0
	v_lshrrev_b32_e32 v0, 8, v20
	v_lshlrev_b32_e32 v2, 3, v2
	v_mul_hi_i32_i24_e32 v1, 0x6000, v0
	v_mul_i32_i24_e32 v0, 0x6000, v0
	v_and_b32_e32 v126, 0x1f8, v2
	v_lshl_add_u64 v[0:1], s[16:17], 0, v[0:1]
	v_lshlrev_b32_e32 v80, 2, v126
	v_mov_b32_e32 v81, 0
	v_lshl_add_u64 v[4:5], v[0:1], 0, s[10:11]
	v_or_b32_e32 v6, 0x800, v80
	v_mov_b32_e32 v7, v81
	v_lshlrev_b32_e32 v102, 3, v20
	v_lshl_add_u64 v[2:3], v[4:5], 0, v[80:81]
	v_lshl_add_u64 v[16:17], v[0:1], 0, v[80:81]
	v_lshl_add_u64 v[18:19], v[4:5], 0, v[6:7]
	v_ashrrev_i32_e32 v103, 31, v102
	global_load_dwordx4 v[82:85], v80, s[46:47] offset:16
	global_load_dwordx4 v[86:89], v80, s[46:47]
	global_load_dwordx4 v[90:93], v[2:3], off offset:16
	global_load_dwordx4 v[94:97], v[2:3], off
	s_nop 0
	global_load_dwordx4 v[0:3], v[16:17], off offset:16
	global_load_dwordx4 v[8:11], v[16:17], off
	global_load_dwordx4 v[112:115], v80, s[46:47] offset:2064
	global_load_dwordx4 v[116:119], v80, s[46:47] offset:2048
	global_load_dwordx4 v[98:101], v[18:19], off offset:16
	global_load_dwordx4 v[120:123], v[18:19], off
	global_load_dwordx4 v[4:7], v[16:17], off offset:2064
	global_load_dwordx4 v[12:15], v[16:17], off offset:2048
	v_lshl_add_u64 v[104:105], s[36:37], 0, v[80:81]
	v_lshlrev_b64 v[16:17], 12, v[102:103]
	v_or_b32_e32 v110, 1, v102
	v_lshl_add_u64 v[16:17], v[104:105], 0, v[16:17]
	v_ashrrev_i32_e32 v111, 31, v110
	global_load_dwordx4 v[76:79], v[16:17], off nt
	global_load_dwordx4 v[72:75], v[16:17], off offset:16 nt
	global_load_dwordx4 v[68:71], v[16:17], off offset:2048 nt
	global_load_dwordx4 v[64:67], v[16:17], off offset:2064 nt
	v_lshlrev_b64 v[16:17], 12, v[110:111]
	v_or_b32_e32 v108, 2, v102
	v_lshl_add_u64 v[16:17], v[104:105], 0, v[16:17]
	v_ashrrev_i32_e32 v109, 31, v108
	global_load_dwordx4 v[60:63], v[16:17], off nt
	global_load_dwordx4 v[56:59], v[16:17], off offset:16 nt
	global_load_dwordx4 v[52:55], v[16:17], off offset:2048 nt
	global_load_dwordx4 v[48:51], v[16:17], off offset:2064 nt
	v_lshlrev_b64 v[16:17], 12, v[108:109]
	v_or_b32_e32 v106, 3, v102
	v_lshl_add_u64 v[16:17], v[104:105], 0, v[16:17]
	v_ashrrev_i32_e32 v107, 31, v106
	global_load_dwordx4 v[44:47], v[16:17], off nt
	global_load_dwordx4 v[40:43], v[16:17], off offset:16 nt
	global_load_dwordx4 v[36:39], v[16:17], off offset:2048 nt
	global_load_dwordx4 v[32:35], v[16:17], off offset:2064 nt
	v_lshlrev_b64 v[16:17], 12, v[106:107]
	v_lshl_add_u64 v[124:125], v[104:105], 0, v[16:17]
	global_load_dwordx4 v[28:31], v[124:125], off nt
	global_load_dwordx4 v[24:27], v[124:125], off offset:16 nt
	global_load_dwordx4 v[20:23], v[124:125], off offset:2048 nt
	global_load_dwordx4 v[16:19], v[124:125], off offset:2064 nt
	v_mbcnt_lo_u32_b32 v80, -1, 0
	v_mbcnt_hi_u32_b32 v80, -1, v80
	s_movk_i32 s12, 0x4000
	s_movk_i32 s13, 0x6000
	s_lshl_b32 s94, s34, 3
	s_add_i32 s97, s95, 0x4000
	s_waitcnt vmcnt(19)
	v_pk_add_f32 v[124:125], v[98:99], 1.0 op_sel_hi:[1,0]
	v_pk_add_f32 v[94:95], v[94:95], 1.0 op_sel_hi:[1,0]
	v_pk_add_f32 v[90:91], v[90:91], 1.0 op_sel_hi:[1,0]
	s_waitcnt vmcnt(18)
	v_pk_add_f32 v[120:121], v[120:121], 1.0 op_sel_hi:[1,0]
	v_pk_mul_f32 v[98:99], v[86:87], v[94:95]
	v_pk_mul_f32 v[94:95], v[82:83], v[90:91]
	v_and_b32_e32 v82, 64, v80
	v_pk_add_f32 v[96:97], v[96:97], 1.0 op_sel_hi:[1,0]
	v_pk_add_f32 v[92:93], v[92:93], 1.0 op_sel_hi:[1,0]
	v_pk_add_f32 v[122:123], v[122:123], 1.0 op_sel_hi:[1,0]
	v_pk_add_f32 v[100:101], v[100:101], 1.0 op_sel_hi:[1,0]
	v_pk_mul_f32 v[90:91], v[116:117], v[120:121]
	v_add_u32_e32 v116, 64, v82
	v_lshlrev_b32_e32 v82, 1, v126
	v_mov_b32_e32 v83, v81
	v_pk_mul_f32 v[96:97], v[88:89], v[96:97]
	v_pk_mul_f32 v[92:93], v[84:85], v[92:93]
	v_pk_mul_f32 v[88:89], v[118:119], v[122:123]
	v_pk_mul_f32 v[84:85], v[114:115], v[100:101]
	v_pk_mul_f32 v[86:87], v[112:113], v[124:125]
	v_lshl_add_u64 v[100:101], s[26:27], 0, v[82:83]
	s_waitcnt vmcnt(15)
	v_mov_b32_e32 v112, v77
	s_waitcnt vmcnt(14)
	v_mov_b32_e32 v113, v73
	v_mov_b32_e32 v82, v76
	v_mov_b32_e32 v83, v72
	v_pk_mul_f32 v[112:113], v[112:113], v[112:113]
	s_waitcnt vmcnt(13)
	v_mov_b32_e32 v114, v69
	v_pk_fma_f32 v[82:83], v[82:83], v[82:83], v[112:113]
	v_mov_b32_e32 v112, v78
	v_mov_b32_e32 v113, v74
	v_pk_fma_f32 v[82:83], v[112:113], v[112:113], v[82:83]
	v_mov_b32_e32 v112, v79
	v_mov_b32_e32 v113, v75
	s_waitcnt vmcnt(12)
	v_mov_b32_e32 v115, v65
	v_pk_fma_f32 v[82:83], v[112:113], v[112:113], v[82:83]
	v_mov_b32_e32 v112, v68
	v_mov_b32_e32 v113, v64
	v_pk_mul_f32 v[114:115], v[114:115], v[114:115]
	v_add_f32_e32 v82, v82, v83
	v_pk_fma_f32 v[112:113], v[112:113], v[112:113], v[114:115]
	v_mov_b32_e32 v114, v70
	v_mov_b32_e32 v115, v66
	v_pk_fma_f32 v[112:113], v[114:115], v[114:115], v[112:113]
	v_mov_b32_e32 v114, v71
	v_mov_b32_e32 v115, v67
	v_xor_b32_e32 v83, 1, v80
	v_pk_fma_f32 v[112:113], v[114:115], v[114:115], v[112:113]
	v_cmp_lt_i32_e32 vcc, v83, v116
	v_add_f32_e32 v82, v82, v112
	v_add_f32_e32 v82, v82, v113
	v_cndmask_b32_e32 v83, v80, v83, vcc
	v_lshlrev_b32_e32 v225, 2, v83
	ds_bpermute_b32 v83, v225, v82
	s_mov_b32 s15, 0x800000
	s_waitcnt vmcnt(10)
	v_mov_b32_e32 v117, v57
	v_mov_b32_e32 v114, v60
	v_mov_b32_e32 v115, v56
	s_waitcnt lgkmcnt(0)
	v_add_f32_e32 v82, v82, v83
	v_xor_b32_e32 v83, 2, v80
	v_cmp_lt_i32_e32 vcc, v83, v116
	s_waitcnt vmcnt(9)
	v_mov_b32_e32 v118, v53
	s_waitcnt vmcnt(8)
; __device__ __forceinline__ void st_bf16x8(bf16_t* p, const f32x4 a, const f32x4 b) { uint4 o; o.x = cvt_pk_bf16(a[0], a[1]); o.y = cvt_pk_bf16(a[2], a[3]); o.z = cvt_pk_bf16(b[0], b[1]); o.w = cvt_pk_bf16(b[2], b[3]); *(uint4*)p = o; }
; __device__ __forceinline__ void p1_prompt_rows(const Params& p) {
;     ...
;         for (int q = 0; q < 4; ++q) { float ss = 0.f;
; #pragma unroll
;             for (int i = 0; i < 4; ++i) ss += v[q][i][0] * v[q][i][0] + v[q][i][1] * v[q][i][1] + v[q][i][2] * v[q][i][2] + v[q][i][3] * v[q][i][3];
; #pragma unroll
;             for (int o = 1; o < 64; o <<= 1) ss += __shfl_xor(ss, o);
;             const float rs = rsqrtf(ss * (1.f / DM) + EPS);
; #pragma unroll
;             for (int h = 0; h < 2; ++h) st_bf16x8(H + (size_t)(rowb + q) * DM + h * 512 + lane * 8, v[q][2 * h] * rs * gs[2 * h] + sh[2 * h], v[q][2 * h + 1] * rs * gs[2 * h + 1] + sh[2 * h + 1]); }
	v_mov_b32_e32 v119, v49
	v_cndmask_b32_e32 v83, v80, v83, vcc
	v_lshlrev_b32_e32 v226, 2, v83
	ds_bpermute_b32 v83, v226, v82
	v_pk_mul_f32 v[118:119], v[118:119], v[118:119]
	v_lshlrev_b64 v[112:113], 11, v[102:103]
	v_lshl_add_u64 v[112:113], v[100:101], 0, v[112:113]
	s_mov_b32 s14, 0x3a800000
	s_waitcnt lgkmcnt(0)
	v_add_f32_e32 v82, v82, v83
	v_xor_b32_e32 v83, 4, v80
	v_cmp_lt_i32_e32 vcc, v83, v116
	s_nop 1
	v_cndmask_b32_e32 v83, v80, v83, vcc
	v_lshlrev_b32_e32 v227, 2, v83
	ds_bpermute_b32 v83, v227, v82
	s_waitcnt lgkmcnt(0)
	v_add_f32_e32 v82, v82, v83
	v_xor_b32_e32 v83, 8, v80
	v_cmp_lt_i32_e32 vcc, v83, v116
	s_nop 1
	v_cndmask_b32_e32 v83, v80, v83, vcc
	v_lshlrev_b32_e32 v228, 2, v83
	ds_bpermute_b32 v83, v228, v82
	s_waitcnt lgkmcnt(0)
	v_add_f32_e32 v82, v82, v83
	v_xor_b32_e32 v83, 16, v80
	v_cmp_lt_i32_e32 vcc, v83, v116
	s_nop 1
	v_cndmask_b32_e32 v83, v80, v83, vcc
	v_lshlrev_b32_e32 v229, 2, v83
	ds_bpermute_b32 v83, v229, v82
	s_waitcnt lgkmcnt(0)
	v_add_f32_e32 v82, v82, v83
	v_xor_b32_e32 v83, 32, v80
	v_cmp_lt_i32_e32 vcc, v83, v116
	v_mov_b32_e32 v116, v61
	v_pk_mul_f32 v[116:117], v[116:117], v[116:117]
	v_cndmask_b32_e32 v80, v80, v83, vcc
	v_lshlrev_b32_e32 v230, 2, v80
	ds_bpermute_b32 v80, v230, v82
	v_pk_fma_f32 v[114:115], v[114:115], v[114:115], v[116:117]
	v_mov_b32_e32 v116, v62
	v_mov_b32_e32 v117, v58
	v_pk_fma_f32 v[114:115], v[116:117], v[116:117], v[114:115]
	s_waitcnt lgkmcnt(0)
	v_add_f32_e32 v80, v82, v80
	v_mov_b32_e32 v82, 0x358637bd
	v_fmamk_f32 v80, v80, 0x3a800000, v82
	v_mul_f32_e32 v83, 0x4b800000, v80
	v_cmp_gt_f32_e32 vcc, s15, v80
	v_mov_b32_e32 v116, v63
	v_mov_b32_e32 v117, v59
	v_cndmask_b32_e32 v80, v80, v83, vcc
	v_rsq_f32_e32 v80, v80
	v_pk_fma_f32 v[114:115], v[116:117], v[116:117], v[114:115]
	v_mov_b32_e32 v116, v52
	v_mov_b32_e32 v117, v48
	v_pk_fma_f32 v[116:117], v[116:117], v[116:117], v[118:119]
	v_mov_b32_e32 v118, v54
	v_mov_b32_e32 v119, v50
	v_mul_f32_e32 v83, 0x45800000, v80
	v_pk_fma_f32 v[116:117], v[118:119], v[118:119], v[116:117]
	v_mov_b32_e32 v118, v55
	v_mov_b32_e32 v119, v51
	v_cndmask_b32_e32 v80, v80, v83, vcc
	v_pk_fma_f32 v[116:117], v[118:119], v[118:119], v[116:117]
	v_add_f32_e32 v83, v114, v115
	v_add_f32_e32 v83, v83, v116
	v_add_f32_e32 v83, v83, v117
	ds_bpermute_b32 v103, v225, v83
	v_pk_mul_f32 v[76:77], v[76:77], v[80:81] op_sel_hi:[1,0]
	v_pk_mul_f32 v[72:73], v[72:73], v[80:81] op_sel_hi:[1,0]
	v_pk_fma_f32 v[76:77], v[98:99], v[76:77], v[8:9]
	v_pk_mul_f32 v[74:75], v[74:75], v[80:81] op_sel_hi:[1,0]
	s_waitcnt lgkmcnt(0)
	v_add_f32_e32 v83, v83, v103
	ds_bpermute_b32 v103, v226, v83
	v_pk_fma_f32 v[114:115], v[92:93], v[74:75], v[2:3]
	v_pk_fma_f32 v[74:75], v[94:95], v[72:73], v[0:1]
	v_cvt_pk_bf16_f32 v72, v76, v77
	v_pk_mul_f32 v[78:79], v[78:79], v[80:81] op_sel_hi:[1,0]
	s_waitcnt lgkmcnt(0)
	v_add_f32_e32 v83, v83, v103
	ds_bpermute_b32 v103, v227, v83
	v_pk_fma_f32 v[78:79], v[96:97], v[78:79], v[10:11]
	v_cvt_pk_bf16_f32 v74, v74, v75
	v_cvt_pk_bf16_f32 v75, v114, v115
	v_pk_mul_f32 v[68:69], v[68:69], v[80:81] op_sel_hi:[1,0]
	s_waitcnt lgkmcnt(0)
	v_add_f32_e32 v76, v83, v103
	ds_bpermute_b32 v77, v228, v76
	v_cvt_pk_bf16_f32 v73, v78, v79
	global_store_dwordx4 v[112:113], v[72:75], off
	v_pk_fma_f32 v[68:69], v[90:91], v[68:69], v[12:13]
	v_pk_mul_f32 v[64:65], v[64:65], v[80:81] op_sel_hi:[1,0]
	s_waitcnt lgkmcnt(0)
	v_add_f32_e32 v72, v76, v77
	ds_bpermute_b32 v73, v229, v72
	v_pk_mul_f32 v[66:67], v[66:67], v[80:81] op_sel_hi:[1,0]
	v_pk_mul_f32 v[70:71], v[70:71], v[80:81] op_sel_hi:[1,0]
	s_waitcnt lgkmcnt(0)
	v_add_f32_e32 v74, v72, v73
	ds_bpermute_b32 v75, v230, v74
	v_pk_fma_f32 v[72:73], v[84:85], v[66:67], v[6:7]
	v_pk_fma_f32 v[66:67], v[86:87], v[64:65], v[4:5]
	v_cvt_pk_bf16_f32 v64, v68, v69
	v_pk_fma_f32 v[70:71], v[88:89], v[70:71], v[14:15]
	s_waitcnt lgkmcnt(0)
	v_add_f32_e32 v68, v74, v75
	v_fmamk_f32 v68, v68, 0x3a800000, v82
	v_mul_f32_e32 v69, 0x4b800000, v68
	v_cmp_gt_f32_e32 vcc, s15, v68
	v_cvt_pk_bf16_f32 v65, v70, v71
	v_cvt_pk_bf16_f32 v66, v66, v67
	v_cvt_pk_bf16_f32 v67, v72, v73
	global_store_dwordx4 v[112:113], v[64:67], off offset:1024
	s_waitcnt vmcnt(9)
	v_mov_b32_e32 v70, v45
	v_cndmask_b32_e32 v68, v68, v69, vcc
	v_rsq_f32_e32 v68, v68
	s_waitcnt vmcnt(8)
	v_mov_b32_e32 v71, v41
	v_mov_b32_e32 v69, v40
	v_pk_mul_f32 v[70:71], v[70:71], v[70:71]
	v_mul_f32_e32 v64, 0x45800000, v68
	v_cndmask_b32_e32 v64, v68, v64, vcc
	v_mov_b32_e32 v68, v44
	v_pk_fma_f32 v[68:69], v[68:69], v[68:69], v[70:71]
	v_mov_b32_e32 v70, v46
	v_mov_b32_e32 v71, v42
	v_pk_fma_f32 v[68:69], v[70:71], v[70:71], v[68:69]
	v_mov_b32_e32 v70, v47
	v_mov_b32_e32 v71, v43
	s_waitcnt vmcnt(7)
	v_mov_b32_e32 v72, v37
	s_waitcnt vmcnt(6)
	v_mov_b32_e32 v73, v33
	v_pk_fma_f32 v[68:69], v[70:71], v[70:71], v[68:69]
	v_mov_b32_e32 v70, v36
	v_mov_b32_e32 v71, v32
	v_pk_mul_f32 v[72:73], v[72:73], v[72:73]
	v_add_f32_e32 v65, v68, v69
	v_pk_fma_f32 v[70:71], v[70:71], v[70:71], v[72:73]
	v_mov_b32_e32 v72, v38
	v_mov_b32_e32 v73, v34
	v_pk_fma_f32 v[70:71], v[72:73], v[72:73], v[70:71]
	v_mov_b32_e32 v72, v39
	v_mov_b32_e32 v73, v35
	v_pk_fma_f32 v[70:71], v[72:73], v[72:73], v[70:71]
	v_lshlrev_b64 v[66:67], 11, v[110:111]
	v_add_f32_e32 v65, v65, v70
	v_add_f32_e32 v65, v65, v71
	ds_bpermute_b32 v68, v225, v65
	v_pk_mul_f32 v[60:61], v[60:61], v[64:65] op_sel_hi:[1,0]
	v_pk_mul_f32 v[62:63], v[62:63], v[64:65] op_sel_hi:[1,0]
	v_pk_fma_f32 v[60:61], v[98:99], v[60:61], v[8:9]
	v_lshl_add_u64 v[66:67], v[100:101], 0, v[66:67]
	s_waitcnt lgkmcnt(0)
; __device__ __forceinline__ void st_bf16x8(bf16_t* p, const f32x4 a, const f32x4 b) { uint4 o; o.x = cvt_pk_bf16(a[0], a[1]); o.y = cvt_pk_bf16(a[2], a[3]); o.z = cvt_pk_bf16(b[0], b[1]); o.w = cvt_pk_bf16(b[2], b[3]); *(uint4*)p = o; }
; __device__ __forceinline__ void p1_prompt_rows(const Params& p) {
;     ...
;         for (int q = 0; q < 4; ++q) { float ss = 0.f;
; #pragma unroll
;             for (int i = 0; i < 4; ++i) ss += v[q][i][0] * v[q][i][0] + v[q][i][1] * v[q][i][1] + v[q][i][2] * v[q][i][2] + v[q][i][3] * v[q][i][3];
; #pragma unroll
;             for (int o = 1; o < 64; o <<= 1) ss += __shfl_xor(ss, o);
;             const float rs = rsqrtf(ss * (1.f / DM) + EPS);
; #pragma unroll
;             for (int h = 0; h < 2; ++h) st_bf16x8(H + (size_t)(rowb + q) * DM + h * 512 + lane * 8, v[q][2 * h] * rs * gs[2 * h] + sh[2 * h], v[q][2 * h + 1] * rs * gs[2 * h + 1] + sh[2 * h + 1]); }
	v_add_f32_e32 v65, v65, v68
	ds_bpermute_b32 v70, v226, v65
	v_pk_mul_f32 v[56:57], v[56:57], v[64:65] op_sel_hi:[1,0]
	v_pk_mul_f32 v[58:59], v[58:59], v[64:65] op_sel_hi:[1,0]
	v_pk_fma_f32 v[62:63], v[96:97], v[62:63], v[10:11]
	v_pk_fma_f32 v[68:69], v[92:93], v[58:59], v[2:3]
	s_waitcnt lgkmcnt(0)
	v_add_f32_e32 v65, v65, v70
	ds_bpermute_b32 v70, v227, v65
	v_pk_fma_f32 v[58:59], v[94:95], v[56:57], v[0:1]
	v_cvt_pk_bf16_f32 v56, v60, v61
	v_cvt_pk_bf16_f32 v57, v62, v63
	v_pk_mul_f32 v[52:53], v[52:53], v[64:65] op_sel_hi:[1,0]
	s_waitcnt lgkmcnt(0)
	v_add_f32_e32 v60, v65, v70
	ds_bpermute_b32 v61, v228, v60
	v_cvt_pk_bf16_f32 v58, v58, v59
	v_cvt_pk_bf16_f32 v59, v68, v69
	global_store_dwordx4 v[66:67], v[56:59], off
	v_pk_fma_f32 v[52:53], v[90:91], v[52:53], v[12:13]
	v_pk_mul_f32 v[48:49], v[48:49], v[64:65] op_sel_hi:[1,0]
	s_waitcnt lgkmcnt(0)
	v_add_f32_e32 v56, v60, v61
	ds_bpermute_b32 v57, v229, v56
	v_pk_mul_f32 v[50:51], v[50:51], v[64:65] op_sel_hi:[1,0]
	v_pk_mul_f32 v[54:55], v[54:55], v[64:65] op_sel_hi:[1,0]
	v_or_b32_e32 v110, 4, v102
	v_pk_fma_f32 v[54:55], v[88:89], v[54:55], v[14:15]
	s_waitcnt lgkmcnt(0)
	v_add_f32_e32 v58, v56, v57
	ds_bpermute_b32 v59, v230, v58
	v_pk_fma_f32 v[56:57], v[84:85], v[50:51], v[6:7]
	v_pk_fma_f32 v[50:51], v[86:87], v[48:49], v[4:5]
	v_cvt_pk_bf16_f32 v48, v52, v53
	v_cvt_pk_bf16_f32 v49, v54, v55
	s_waitcnt lgkmcnt(0)
	v_add_f32_e32 v52, v58, v59
	v_fmamk_f32 v52, v52, 0x3a800000, v82
	v_mul_f32_e32 v53, 0x4b800000, v52
	v_cmp_gt_f32_e32 vcc, s15, v52
	v_cvt_pk_bf16_f32 v50, v50, v51
	v_cvt_pk_bf16_f32 v51, v56, v57
	global_store_dwordx4 v[66:67], v[48:51], off offset:1024
	s_waitcnt vmcnt(7)
	v_mov_b32_e32 v54, v29
	v_cndmask_b32_e32 v52, v52, v53, vcc
	v_rsq_f32_e32 v52, v52
	s_waitcnt vmcnt(6)
	v_mov_b32_e32 v55, v25
	v_mov_b32_e32 v53, v24
	v_pk_mul_f32 v[54:55], v[54:55], v[54:55]
	v_mul_f32_e32 v48, 0x45800000, v52
	v_cndmask_b32_e32 v48, v52, v48, vcc
	v_mov_b32_e32 v52, v28
	v_pk_fma_f32 v[52:53], v[52:53], v[52:53], v[54:55]
	v_mov_b32_e32 v54, v30
	v_mov_b32_e32 v55, v26
	v_pk_fma_f32 v[52:53], v[54:55], v[54:55], v[52:53]
	v_mov_b32_e32 v54, v31
	v_mov_b32_e32 v55, v27
	s_waitcnt vmcnt(5)
	v_mov_b32_e32 v56, v21
	s_waitcnt vmcnt(4)
	v_mov_b32_e32 v57, v17
	v_pk_fma_f32 v[52:53], v[54:55], v[54:55], v[52:53]
	v_mov_b32_e32 v54, v20
	v_mov_b32_e32 v55, v16
	v_pk_mul_f32 v[56:57], v[56:57], v[56:57]
	v_add_f32_e32 v49, v52, v53
	v_pk_fma_f32 v[54:55], v[54:55], v[54:55], v[56:57]
	v_mov_b32_e32 v56, v22
	v_mov_b32_e32 v57, v18
	v_pk_fma_f32 v[54:55], v[56:57], v[56:57], v[54:55]
	v_mov_b32_e32 v56, v23
	v_mov_b32_e32 v57, v19
	v_pk_fma_f32 v[54:55], v[56:57], v[56:57], v[54:55]
	v_lshlrev_b64 v[50:51], 11, v[108:109]
	v_add_f32_e32 v49, v49, v54
	v_add_f32_e32 v49, v49, v55
	ds_bpermute_b32 v52, v225, v49
	v_pk_mul_f32 v[44:45], v[44:45], v[48:49] op_sel_hi:[1,0]
	v_pk_mul_f32 v[46:47], v[46:47], v[48:49] op_sel_hi:[1,0]
	v_pk_fma_f32 v[44:45], v[98:99], v[44:45], v[8:9]
	v_lshl_add_u64 v[50:51], v[100:101], 0, v[50:51]
	s_waitcnt lgkmcnt(0)
	v_add_f32_e32 v49, v49, v52
	ds_bpermute_b32 v54, v226, v49
	v_pk_mul_f32 v[40:41], v[40:41], v[48:49] op_sel_hi:[1,0]
	v_pk_mul_f32 v[42:43], v[42:43], v[48:49] op_sel_hi:[1,0]
	v_pk_fma_f32 v[46:47], v[96:97], v[46:47], v[10:11]
	v_pk_fma_f32 v[52:53], v[92:93], v[42:43], v[2:3]
	s_waitcnt lgkmcnt(0)
	v_add_f32_e32 v49, v49, v54
	ds_bpermute_b32 v54, v227, v49
	v_pk_fma_f32 v[42:43], v[94:95], v[40:41], v[0:1]
	v_cvt_pk_bf16_f32 v40, v44, v45
	v_cvt_pk_bf16_f32 v41, v46, v47
	v_pk_mul_f32 v[36:37], v[36:37], v[48:49] op_sel_hi:[1,0]
	s_waitcnt lgkmcnt(0)
	v_add_f32_e32 v44, v49, v54
	ds_bpermute_b32 v45, v228, v44
	v_cvt_pk_bf16_f32 v42, v42, v43
	v_cvt_pk_bf16_f32 v43, v52, v53
	global_store_dwordx4 v[50:51], v[40:43], off
	v_pk_fma_f32 v[36:37], v[90:91], v[36:37], v[12:13]
	v_pk_mul_f32 v[32:33], v[32:33], v[48:49] op_sel_hi:[1,0]
	s_waitcnt lgkmcnt(0)
	v_add_f32_e32 v40, v44, v45
	ds_bpermute_b32 v41, v229, v40
	v_pk_mul_f32 v[34:35], v[34:35], v[48:49] op_sel_hi:[1,0]
	v_pk_mul_f32 v[38:39], v[38:39], v[48:49] op_sel_hi:[1,0]
	v_ashrrev_i32_e32 v111, 31, v110
	v_pk_fma_f32 v[38:39], v[88:89], v[38:39], v[14:15]
	s_waitcnt lgkmcnt(0)
	v_add_f32_e32 v42, v40, v41
	ds_bpermute_b32 v43, v230, v42
	v_pk_fma_f32 v[40:41], v[84:85], v[34:35], v[6:7]
	v_pk_fma_f32 v[34:35], v[86:87], v[32:33], v[4:5]
	v_cvt_pk_bf16_f32 v32, v36, v37
	v_cvt_pk_bf16_f32 v33, v38, v39
	s_waitcnt lgkmcnt(0)
; __device__ __forceinline__ void st_bf16x8(bf16_t* p, const f32x4 a, const f32x4 b) { uint4 o; o.x = cvt_pk_bf16(a[0], a[1]); o.y = cvt_pk_bf16(a[2], a[3]); o.z = cvt_pk_bf16(b[0], b[1]); o.w = cvt_pk_bf16(b[2], b[3]); *(uint4*)p = o; }
; __device__ __forceinline__ void p1_prompt_rows(const Params& p) {
;     ...
;     for (int trip = 0; trip < 2; ++trip) { const int rowb = gw * 8 + trip * 4;
;         f32x4 v[4][4];
; #pragma unroll
;         for (int q = 0; q < 4; ++q)
; #pragma unroll
;             for (int i = 0; i < 4; ++i) v[q][i] = *(const f32x4*)(p.x_prompt + (size_t)(rowb + q) * DM + (i >> 1) * 512 + lane * 8 + (i & 1) * 4);
;         __builtin_amdgcn_sched_barrier(0);
; #pragma unroll
;         for (int q = 0; q < 4; ++q) { float ss = 0.f;
; #pragma unroll
;             for (int i = 0; i < 4; ++i) ss += v[q][i][0] * v[q][i][0] + v[q][i][1] * v[q][i][1] + v[q][i][2] * v[q][i][2] + v[q][i][3] * v[q][i][3];
; #pragma unroll
;             for (int o = 1; o < 64; o <<= 1) ss += __shfl_xor(ss, o);
;             const float rs = rsqrtf(ss * (1.f / DM) + EPS);
; #pragma unroll
;             for (int h = 0; h < 2; ++h) st_bf16x8(H + (size_t)(rowb + q) * DM + h * 512 + lane * 8, v[q][2 * h] * rs * gs[2 * h] + sh[2 * h], v[q][2 * h + 1] * rs * gs[2 * h + 1] + sh[2 * h + 1]); }
	v_add_f32_e32 v36, v42, v43
	v_fmamk_f32 v36, v36, 0x3a800000, v82
	v_mul_f32_e32 v37, 0x4b800000, v36
	v_cmp_gt_f32_e32 vcc, s15, v36
	v_cvt_pk_bf16_f32 v34, v34, v35
	v_cvt_pk_bf16_f32 v35, v40, v41
	global_store_dwordx4 v[50:51], v[32:35], off offset:1024
	v_or_b32_e32 v112, 5, v102
	v_cndmask_b32_e32 v36, v36, v37, vcc
	v_rsq_f32_e32 v36, v36
	v_lshlrev_b64 v[34:35], 11, v[106:107]
	v_lshl_add_u64 v[34:35], v[100:101], 0, v[34:35]
	v_ashrrev_i32_e32 v113, 31, v112
	v_mul_f32_e32 v32, 0x45800000, v36
	v_cndmask_b32_e32 v32, v36, v32, vcc
	v_pk_mul_f32 v[28:29], v[28:29], v[32:33] op_sel_hi:[1,0]
	v_pk_mul_f32 v[30:31], v[30:31], v[32:33] op_sel_hi:[1,0]
	v_pk_mul_f32 v[24:25], v[24:25], v[32:33] op_sel_hi:[1,0]
	v_pk_mul_f32 v[26:27], v[26:27], v[32:33] op_sel_hi:[1,0]
	v_pk_fma_f32 v[30:31], v[96:97], v[30:31], v[10:11]
	v_pk_fma_f32 v[28:29], v[98:99], v[28:29], v[8:9]
	v_pk_fma_f32 v[36:37], v[92:93], v[26:27], v[2:3]
	v_pk_fma_f32 v[26:27], v[94:95], v[24:25], v[0:1]
	v_cvt_pk_bf16_f32 v24, v28, v29
	v_cvt_pk_bf16_f32 v25, v30, v31
	v_pk_mul_f32 v[20:21], v[20:21], v[32:33] op_sel_hi:[1,0]
	v_pk_mul_f32 v[22:23], v[22:23], v[32:33] op_sel_hi:[1,0]
	v_pk_mul_f32 v[16:17], v[16:17], v[32:33] op_sel_hi:[1,0]
	v_pk_mul_f32 v[18:19], v[18:19], v[32:33] op_sel_hi:[1,0]
	v_cvt_pk_bf16_f32 v26, v26, v27
	v_cvt_pk_bf16_f32 v27, v36, v37
	global_store_dwordx4 v[34:35], v[24:27], off
	v_pk_fma_f32 v[22:23], v[88:89], v[22:23], v[14:15]
	v_pk_fma_f32 v[20:21], v[90:91], v[20:21], v[12:13]
	v_pk_fma_f32 v[24:25], v[84:85], v[18:19], v[6:7]
	v_pk_fma_f32 v[18:19], v[86:87], v[16:17], v[4:5]
	v_cvt_pk_bf16_f32 v16, v20, v21
	v_cvt_pk_bf16_f32 v17, v22, v23
	v_or_b32_e32 v66, 6, v102
	v_cvt_pk_bf16_f32 v18, v18, v19
	v_cvt_pk_bf16_f32 v19, v24, v25
	global_store_dwordx4 v[34:35], v[16:19], off offset:1024
	v_ashrrev_i32_e32 v67, 31, v66
	v_or_b32_e32 v64, 7, v102
	v_lshlrev_b64 v[16:17], 12, v[110:111]
	v_lshl_add_u64 v[16:17], v[104:105], 0, v[16:17]
	global_load_dwordx4 v[68:71], v[16:17], off nt
	global_load_dwordx4 v[72:75], v[16:17], off offset:16 nt
	global_load_dwordx4 v[76:79], v[16:17], off offset:2048 nt
	global_load_dwordx4 v[106:109], v[16:17], off offset:2064 nt
	v_lshlrev_b64 v[16:17], 12, v[112:113]
	v_lshl_add_u64 v[16:17], v[104:105], 0, v[16:17]
	global_load_dwordx4 v[60:63], v[16:17], off nt
	global_load_dwordx4 v[56:59], v[16:17], off offset:16 nt
	global_load_dwordx4 v[52:55], v[16:17], off offset:2048 nt
	global_load_dwordx4 v[48:51], v[16:17], off offset:2064 nt
	v_lshlrev_b64 v[16:17], 12, v[66:67]
	v_lshl_add_u64 v[16:17], v[104:105], 0, v[16:17]
	v_ashrrev_i32_e32 v65, 31, v64
	global_load_dwordx4 v[44:47], v[16:17], off nt
	global_load_dwordx4 v[40:43], v[16:17], off offset:16 nt
	global_load_dwordx4 v[36:39], v[16:17], off offset:2048 nt
	global_load_dwordx4 v[32:35], v[16:17], off offset:2064 nt
	v_lshlrev_b64 v[16:17], 12, v[64:65]
	v_lshl_add_u64 v[16:17], v[104:105], 0, v[16:17]
	global_load_dwordx4 v[28:31], v[16:17], off nt
	global_load_dwordx4 v[24:27], v[16:17], off offset:16 nt
	global_load_dwordx4 v[20:23], v[16:17], off offset:2048 nt
	s_nop 0
	global_load_dwordx4 v[16:19], v[16:17], off offset:2064 nt
	s_waitcnt vmcnt(15)
	v_mov_b32_e32 v104, v69
	s_waitcnt vmcnt(14)
	v_mov_b32_e32 v105, v73
	v_mov_b32_e32 v102, v68
	v_mov_b32_e32 v103, v72
	v_pk_mul_f32 v[104:105], v[104:105], v[104:105]
	s_waitcnt vmcnt(13)
	v_mov_b32_e32 v114, v77
	v_pk_fma_f32 v[102:103], v[102:103], v[102:103], v[104:105]
	v_mov_b32_e32 v104, v70
	v_mov_b32_e32 v105, v74
	v_pk_fma_f32 v[102:103], v[104:105], v[104:105], v[102:103]
	v_mov_b32_e32 v104, v71
	v_mov_b32_e32 v105, v75
	s_waitcnt vmcnt(12)
	v_mov_b32_e32 v115, v107
	v_pk_fma_f32 v[102:103], v[104:105], v[104:105], v[102:103]
	v_mov_b32_e32 v104, v76
	v_mov_b32_e32 v105, v106
	v_pk_mul_f32 v[114:115], v[114:115], v[114:115]
	v_add_f32_e32 v80, v102, v103
	v_pk_fma_f32 v[104:105], v[104:105], v[104:105], v[114:115]
	v_mov_b32_e32 v114, v78
	v_mov_b32_e32 v115, v108
	v_pk_fma_f32 v[104:105], v[114:115], v[114:115], v[104:105]
	v_mov_b32_e32 v114, v79
	v_mov_b32_e32 v115, v109
	v_pk_fma_f32 v[104:105], v[114:115], v[114:115], v[104:105]
	v_lshlrev_b64 v[102:103], 11, v[110:111]
	v_add_f32_e32 v80, v80, v104
	v_add_f32_e32 v80, v80, v105
	ds_bpermute_b32 v83, v225, v80
	s_waitcnt vmcnt(11)
	v_mov_b32_e32 v110, v61
	s_waitcnt vmcnt(10)
	v_mov_b32_e32 v111, v57
	v_mov_b32_e32 v104, v60
	v_mov_b32_e32 v105, v56
	s_waitcnt lgkmcnt(0)
	v_add_f32_e32 v80, v80, v83
	ds_bpermute_b32 v83, v226, v80
	v_pk_mul_f32 v[110:111], v[110:111], v[110:111]
	s_waitcnt vmcnt(9)
	v_mov_b32_e32 v114, v53
	v_pk_fma_f32 v[104:105], v[104:105], v[104:105], v[110:111]
	v_mov_b32_e32 v110, v62
	s_waitcnt lgkmcnt(0)
	v_add_f32_e32 v80, v80, v83
	ds_bpermute_b32 v83, v227, v80
	v_mov_b32_e32 v111, v58
	v_pk_fma_f32 v[104:105], v[110:111], v[110:111], v[104:105]
	v_mov_b32_e32 v110, v63
	v_mov_b32_e32 v111, v59
	s_waitcnt lgkmcnt(0)
	v_add_f32_e32 v80, v80, v83
	ds_bpermute_b32 v83, v228, v80
	s_waitcnt vmcnt(8)
	v_mov_b32_e32 v115, v49
	v_pk_fma_f32 v[104:105], v[110:111], v[110:111], v[104:105]
	v_mov_b32_e32 v110, v52
	v_mov_b32_e32 v111, v48
	s_waitcnt lgkmcnt(0)
	v_add_f32_e32 v80, v80, v83
	ds_bpermute_b32 v83, v229, v80
	v_pk_mul_f32 v[114:115], v[114:115], v[114:115]
	v_lshl_add_u64 v[102:103], v[100:101], 0, v[102:103]
	v_pk_fma_f32 v[110:111], v[110:111], v[110:111], v[114:115]
	v_mov_b32_e32 v114, v54
	s_waitcnt lgkmcnt(0)
	v_add_f32_e32 v80, v80, v83
	ds_bpermute_b32 v83, v230, v80
	v_mov_b32_e32 v115, v50
	v_pk_fma_f32 v[110:111], v[114:115], v[114:115], v[110:111]
	v_mov_b32_e32 v114, v55
	v_mov_b32_e32 v115, v51
	s_waitcnt lgkmcnt(0)
; __device__ __forceinline__ void st_bf16x8(bf16_t* p, const f32x4 a, const f32x4 b) { uint4 o; o.x = cvt_pk_bf16(a[0], a[1]); o.y = cvt_pk_bf16(a[2], a[3]); o.z = cvt_pk_bf16(b[0], b[1]); o.w = cvt_pk_bf16(b[2], b[3]); *(uint4*)p = o; }
; __device__ __forceinline__ void p1_prompt_rows(const Params& p) {
;     ...
;         for (int q = 0; q < 4; ++q) { float ss = 0.f;
; #pragma unroll
;             for (int i = 0; i < 4; ++i) ss += v[q][i][0] * v[q][i][0] + v[q][i][1] * v[q][i][1] + v[q][i][2] * v[q][i][2] + v[q][i][3] * v[q][i][3];
; #pragma unroll
;             for (int o = 1; o < 64; o <<= 1) ss += __shfl_xor(ss, o);
;             const float rs = rsqrtf(ss * (1.f / DM) + EPS);
; #pragma unroll
;             for (int h = 0; h < 2; ++h) st_bf16x8(H + (size_t)(rowb + q) * DM + h * 512 + lane * 8, v[q][2 * h] * rs * gs[2 * h] + sh[2 * h], v[q][2 * h + 1] * rs * gs[2 * h + 1] + sh[2 * h + 1]); }
	v_add_f32_e32 v80, v80, v83
	v_fmamk_f32 v80, v80, 0x3a800000, v82
	v_mul_f32_e32 v83, 0x4b800000, v80
	v_cmp_gt_f32_e32 vcc, s15, v80
	v_pk_fma_f32 v[110:111], v[114:115], v[114:115], v[110:111]
	s_movk_i32 s33, 0x4080
	v_cndmask_b32_e32 v80, v80, v83, vcc
	v_rsq_f32_e32 v80, v80
	s_nop 0
	v_mul_f32_e32 v83, 0x45800000, v80
	v_cndmask_b32_e32 v80, v80, v83, vcc
	v_add_f32_e32 v83, v104, v105
	v_add_f32_e32 v83, v83, v110
	v_add_f32_e32 v83, v83, v111
	ds_bpermute_b32 v104, v225, v83
	v_pk_mul_f32 v[68:69], v[68:69], v[80:81] op_sel_hi:[1,0]
	v_pk_mul_f32 v[70:71], v[70:71], v[80:81] op_sel_hi:[1,0]
	v_pk_mul_f32 v[72:73], v[72:73], v[80:81] op_sel_hi:[1,0]
	v_pk_fma_f32 v[70:71], v[96:97], v[70:71], v[10:11]
	s_waitcnt lgkmcnt(0)
	v_add_f32_e32 v83, v83, v104
	ds_bpermute_b32 v104, v226, v83
	v_pk_fma_f32 v[68:69], v[98:99], v[68:69], v[8:9]
	v_pk_fma_f32 v[72:73], v[94:95], v[72:73], v[0:1]
	v_cvt_pk_bf16_f32 v68, v68, v69
	v_cvt_pk_bf16_f32 v69, v70, v71
	s_waitcnt lgkmcnt(0)
	v_add_f32_e32 v83, v83, v104
	ds_bpermute_b32 v104, v227, v83
	v_cvt_pk_bf16_f32 v70, v72, v73
	v_pk_mul_f32 v[74:75], v[74:75], v[80:81] op_sel_hi:[1,0]
	s_waitcnt lgkmcnt(0)
	v_add_f32_e32 v72, v83, v104
	ds_bpermute_b32 v73, v228, v72
	v_pk_fma_f32 v[74:75], v[92:93], v[74:75], v[2:3]
	s_nop 0
	v_cvt_pk_bf16_f32 v71, v74, v75
	global_store_dwordx4 v[102:103], v[68:71], off
	v_pk_mul_f32 v[74:75], v[108:109], v[80:81] op_sel_hi:[1,0]
	s_nop 0
	v_pk_mul_f32 v[68:69], v[76:77], v[80:81] op_sel_hi:[1,0]
	s_waitcnt lgkmcnt(0)
	v_add_f32_e32 v76, v72, v73
	ds_bpermute_b32 v77, v229, v76
	v_pk_mul_f32 v[70:71], v[78:79], v[80:81] op_sel_hi:[1,0]
	v_pk_fma_f32 v[68:69], v[90:91], v[68:69], v[12:13]
	v_pk_fma_f32 v[70:71], v[88:89], v[70:71], v[14:15]
	v_cvt_pk_bf16_f32 v68, v68, v69
	s_waitcnt lgkmcnt(0)
	v_add_f32_e32 v76, v76, v77
	ds_bpermute_b32 v77, v230, v76
	v_cvt_pk_bf16_f32 v69, v70, v71
	v_pk_mul_f32 v[72:73], v[106:107], v[80:81] op_sel_hi:[1,0]
	v_pk_fma_f32 v[74:75], v[84:85], v[74:75], v[6:7]
	v_pk_fma_f32 v[72:73], v[86:87], v[72:73], v[4:5]
	s_waitcnt lgkmcnt(0)
	v_add_f32_e32 v70, v76, v77
	v_fmamk_f32 v70, v70, 0x3a800000, v82
	v_mul_f32_e32 v71, 0x4b800000, v70
	v_cmp_gt_f32_e32 vcc, s15, v70
	s_waitcnt vmcnt(5)
	v_mov_b32_e32 v77, v33
	v_cndmask_b32_e32 v70, v70, v71, vcc
	v_rsq_f32_e32 v76, v70
	v_cvt_pk_bf16_f32 v71, v74, v75
	v_mov_b32_e32 v74, v45
	v_mov_b32_e32 v75, v41
	v_cvt_pk_bf16_f32 v70, v72, v73
	v_mov_b32_e32 v72, v44
	v_mov_b32_e32 v73, v40
	v_pk_mul_f32 v[74:75], v[74:75], v[74:75]
	global_store_dwordx4 v[102:103], v[68:71], off offset:1024
	v_pk_fma_f32 v[72:73], v[72:73], v[72:73], v[74:75]
	v_mov_b32_e32 v74, v46
	v_mul_f32_e32 v68, 0x45800000, v76
	v_mov_b32_e32 v75, v42
	v_cndmask_b32_e32 v68, v76, v68, vcc
	v_pk_fma_f32 v[72:73], v[74:75], v[74:75], v[72:73]
	v_mov_b32_e32 v74, v47
	v_mov_b32_e32 v75, v43
	v_mov_b32_e32 v76, v37
	v_pk_fma_f32 v[72:73], v[74:75], v[74:75], v[72:73]
	v_mov_b32_e32 v74, v36
	v_mov_b32_e32 v75, v32
	v_pk_mul_f32 v[76:77], v[76:77], v[76:77]
	v_add_f32_e32 v69, v72, v73
	v_pk_fma_f32 v[74:75], v[74:75], v[74:75], v[76:77]
	v_mov_b32_e32 v76, v38
	v_mov_b32_e32 v77, v34
	v_pk_fma_f32 v[74:75], v[76:77], v[76:77], v[74:75]
	v_mov_b32_e32 v76, v39
	v_mov_b32_e32 v77, v35
	v_pk_fma_f32 v[74:75], v[76:77], v[76:77], v[74:75]
	v_lshlrev_b64 v[70:71], 11, v[112:113]
	v_add_f32_e32 v69, v69, v74
	v_add_f32_e32 v69, v69, v75
	ds_bpermute_b32 v72, v225, v69
	v_pk_mul_f32 v[60:61], v[60:61], v[68:69] op_sel_hi:[1,0]
	v_pk_mul_f32 v[62:63], v[62:63], v[68:69] op_sel_hi:[1,0]
	v_pk_fma_f32 v[60:61], v[98:99], v[60:61], v[8:9]
	v_lshl_add_u64 v[70:71], v[100:101], 0, v[70:71]
	s_waitcnt lgkmcnt(0)
	v_add_f32_e32 v69, v69, v72
	ds_bpermute_b32 v74, v226, v69
	v_pk_mul_f32 v[56:57], v[56:57], v[68:69] op_sel_hi:[1,0]
	v_pk_mul_f32 v[58:59], v[58:59], v[68:69] op_sel_hi:[1,0]
	v_pk_fma_f32 v[62:63], v[96:97], v[62:63], v[10:11]
	v_pk_fma_f32 v[72:73], v[92:93], v[58:59], v[2:3]
	s_waitcnt lgkmcnt(0)
	v_add_f32_e32 v69, v69, v74
	ds_bpermute_b32 v74, v227, v69
	v_pk_fma_f32 v[58:59], v[94:95], v[56:57], v[0:1]
	v_cvt_pk_bf16_f32 v56, v60, v61
	v_cvt_pk_bf16_f32 v57, v62, v63
	v_pk_mul_f32 v[52:53], v[52:53], v[68:69] op_sel_hi:[1,0]
	s_waitcnt lgkmcnt(0)
	v_add_f32_e32 v60, v69, v74
	ds_bpermute_b32 v61, v228, v60
	v_cvt_pk_bf16_f32 v58, v58, v59
	v_cvt_pk_bf16_f32 v59, v72, v73
	global_store_dwordx4 v[70:71], v[56:59], off
	v_pk_fma_f32 v[52:53], v[90:91], v[52:53], v[12:13]
	v_pk_mul_f32 v[48:49], v[48:49], v[68:69] op_sel_hi:[1,0]
	s_waitcnt lgkmcnt(0)
	v_add_f32_e32 v56, v60, v61
	ds_bpermute_b32 v57, v229, v56
	v_pk_mul_f32 v[50:51], v[50:51], v[68:69] op_sel_hi:[1,0]
	v_pk_mul_f32 v[54:55], v[54:55], v[68:69] op_sel_hi:[1,0]
	s_waitcnt lgkmcnt(0)
	v_add_f32_e32 v58, v56, v57
	ds_bpermute_b32 v59, v230, v58
	v_pk_fma_f32 v[56:57], v[84:85], v[50:51], v[6:7]
	v_pk_fma_f32 v[50:51], v[86:87], v[48:49], v[4:5]
	v_cvt_pk_bf16_f32 v48, v52, v53
	v_pk_fma_f32 v[54:55], v[88:89], v[54:55], v[14:15]
	s_waitcnt lgkmcnt(0)
	v_add_f32_e32 v52, v58, v59
	v_fmamk_f32 v52, v52, 0x3a800000, v82
	v_mul_f32_e32 v53, 0x4b800000, v52
	v_cmp_gt_f32_e32 vcc, s15, v52
	v_cvt_pk_bf16_f32 v49, v54, v55
	v_cvt_pk_bf16_f32 v50, v50, v51
	v_cvt_pk_bf16_f32 v51, v56, v57
	global_store_dwordx4 v[70:71], v[48:51], off offset:1024
	s_waitcnt vmcnt(7)
	v_mov_b32_e32 v54, v29
	v_cndmask_b32_e32 v52, v52, v53, vcc
	v_rsq_f32_e32 v52, v52
	s_waitcnt vmcnt(6)
; __device__ __forceinline__ int fresh_tid() { int t = threadIdx.x; asm volatile("" : "+v"(t)); return t; }
; __device__ __forceinline__ void st_bf16x8(bf16_t* p, const f32x4 a, const f32x4 b) { uint4 o; o.x = cvt_pk_bf16(a[0], a[1]); o.y = cvt_pk_bf16(a[2], a[3]); o.z = cvt_pk_bf16(b[0], b[1]); o.w = cvt_pk_bf16(b[2], b[3]); *(uint4*)p = o; }
;     const int tid = fresh_tid(), lane = tid & 63, gw = blockIdx.x * 8 + (tid >> 6), nw = (nblk ? nblk : (int)gridDim.x) * 8;
;     const float* mod = (const float*)(p.ws + WS_MOD); bf16_t* H = (bf16_t*)(p.ws + WS_H);
;     f32x4 gv[4];
; #pragma unroll
;     for (int i = 0; i < 4; ++i) gv[i] = *(const f32x4*)(g + (i >> 1) * 512 + lane * 8 + (i & 1) * 4);
;     for (int rowb = r0 + gw; rowb < r1; rowb += 4 * nw) {
;         f32x4 v[4][4];
; #pragma unroll
;         for (int q = 0; q < 4; ++q) { const int row = rowb + q * nw;
;             if (row < r1) { const float* src = from_out ? p.out + (size_t)row * DM : (row < NP ? p.x_prompt + (size_t)row * DM : p.x_sample + (size_t)(row - NP) * DM);
; #pragma unroll
;                 for (int i = 0; i < 4; ++i) v[q][i] = *(const f32x4*)(src + (i >> 1) * 512 + lane * 8 + (i & 1) * 4); }
; __device__ __forceinline__ void p1_prompt_rows(const Params& p) {
;     ...
;             const float rs = rsqrtf(ss * (1.f / DM) + EPS);
; #pragma unroll
;             for (int h = 0; h < 2; ++h) st_bf16x8(H + (size_t)(rowb + q) * DM + h * 512 + lane * 8, v[q][2 * h] * rs * gs[2 * h] + sh[2 * h], v[q][2 * h + 1] * rs * gs[2 * h + 1] + sh[2 * h + 1]); }
	v_mov_b32_e32 v55, v25
	v_mov_b32_e32 v53, v24
	v_pk_mul_f32 v[54:55], v[54:55], v[54:55]
	v_mul_f32_e32 v48, 0x45800000, v52
	v_cndmask_b32_e32 v48, v52, v48, vcc
	v_mov_b32_e32 v52, v28
	v_pk_fma_f32 v[52:53], v[52:53], v[52:53], v[54:55]
	v_mov_b32_e32 v54, v30
	v_mov_b32_e32 v55, v26
	v_pk_fma_f32 v[52:53], v[54:55], v[54:55], v[52:53]
	v_mov_b32_e32 v54, v31
	v_mov_b32_e32 v55, v27
	s_waitcnt vmcnt(5)
	v_mov_b32_e32 v56, v21
	s_waitcnt vmcnt(4)
	v_mov_b32_e32 v57, v17
	v_pk_fma_f32 v[52:53], v[54:55], v[54:55], v[52:53]
	v_mov_b32_e32 v54, v20
	v_mov_b32_e32 v55, v16
	v_pk_mul_f32 v[56:57], v[56:57], v[56:57]
	v_add_f32_e32 v49, v52, v53
	v_pk_fma_f32 v[54:55], v[54:55], v[54:55], v[56:57]
	v_mov_b32_e32 v56, v22
	v_mov_b32_e32 v57, v18
	v_pk_fma_f32 v[54:55], v[56:57], v[56:57], v[54:55]
	v_mov_b32_e32 v56, v23
	v_mov_b32_e32 v57, v19
	v_pk_fma_f32 v[54:55], v[56:57], v[56:57], v[54:55]
	v_lshlrev_b64 v[50:51], 11, v[66:67]
	v_add_f32_e32 v49, v49, v54
	v_add_f32_e32 v49, v49, v55
	ds_bpermute_b32 v52, v225, v49
	v_pk_mul_f32 v[44:45], v[44:45], v[48:49] op_sel_hi:[1,0]
	v_pk_mul_f32 v[46:47], v[46:47], v[48:49] op_sel_hi:[1,0]
	v_pk_fma_f32 v[44:45], v[98:99], v[44:45], v[8:9]
	v_lshl_add_u64 v[50:51], v[100:101], 0, v[50:51]
	s_waitcnt lgkmcnt(0)
	v_add_f32_e32 v49, v49, v52
	ds_bpermute_b32 v54, v226, v49
	v_pk_mul_f32 v[40:41], v[40:41], v[48:49] op_sel_hi:[1,0]
	v_pk_mul_f32 v[42:43], v[42:43], v[48:49] op_sel_hi:[1,0]
	v_pk_fma_f32 v[46:47], v[96:97], v[46:47], v[10:11]
	v_pk_fma_f32 v[52:53], v[92:93], v[42:43], v[2:3]
	s_waitcnt lgkmcnt(0)
	v_add_f32_e32 v49, v49, v54
	ds_bpermute_b32 v54, v227, v49
	v_pk_fma_f32 v[42:43], v[94:95], v[40:41], v[0:1]
	v_cvt_pk_bf16_f32 v40, v44, v45
	v_cvt_pk_bf16_f32 v41, v46, v47
	v_pk_mul_f32 v[36:37], v[36:37], v[48:49] op_sel_hi:[1,0]
	s_waitcnt lgkmcnt(0)
	v_add_f32_e32 v44, v49, v54
	ds_bpermute_b32 v45, v228, v44
	v_cvt_pk_bf16_f32 v42, v42, v43
	v_cvt_pk_bf16_f32 v43, v52, v53
	global_store_dwordx4 v[50:51], v[40:43], off
	v_pk_fma_f32 v[36:37], v[90:91], v[36:37], v[12:13]
	v_pk_mul_f32 v[32:33], v[32:33], v[48:49] op_sel_hi:[1,0]
	s_waitcnt lgkmcnt(0)
	v_add_f32_e32 v40, v44, v45
	ds_bpermute_b32 v41, v229, v40
	v_pk_mul_f32 v[34:35], v[34:35], v[48:49] op_sel_hi:[1,0]
	v_pk_mul_f32 v[38:39], v[38:39], v[48:49] op_sel_hi:[1,0]
	s_waitcnt lgkmcnt(0)
	v_add_f32_e32 v42, v40, v41
	ds_bpermute_b32 v43, v230, v42
	v_pk_fma_f32 v[40:41], v[84:85], v[34:35], v[6:7]
	v_pk_fma_f32 v[34:35], v[86:87], v[32:33], v[4:5]
	v_cvt_pk_bf16_f32 v32, v36, v37
	v_pk_fma_f32 v[38:39], v[88:89], v[38:39], v[14:15]
	s_waitcnt lgkmcnt(0)
	v_add_f32_e32 v36, v42, v43
	v_fmamk_f32 v36, v36, 0x3a800000, v82
	v_mul_f32_e32 v37, 0x4b800000, v36
	v_cmp_gt_f32_e32 vcc, s15, v36
	v_cvt_pk_bf16_f32 v33, v38, v39
	v_cvt_pk_bf16_f32 v34, v34, v35
	v_cvt_pk_bf16_f32 v35, v40, v41
	global_store_dwordx4 v[50:51], v[32:35], off offset:1024
	s_nop 0
	v_cndmask_b32_e32 v36, v36, v37, vcc
	v_rsq_f32_e32 v36, v36
	v_lshlrev_b64 v[34:35], 11, v[64:65]
	v_lshl_add_u64 v[34:35], v[100:101], 0, v[34:35]
	v_mul_f32_e32 v32, 0x45800000, v36
	v_cndmask_b32_e32 v32, v36, v32, vcc
	v_pk_mul_f32 v[24:25], v[24:25], v[32:33] op_sel_hi:[1,0]
	v_pk_mul_f32 v[26:27], v[26:27], v[32:33] op_sel_hi:[1,0]
	v_pk_mul_f32 v[28:29], v[28:29], v[32:33] op_sel_hi:[1,0]
	v_pk_mul_f32 v[30:31], v[30:31], v[32:33] op_sel_hi:[1,0]
	v_pk_fma_f32 v[26:27], v[92:93], v[26:27], v[2:3]
	v_pk_fma_f32 v[2:3], v[94:95], v[24:25], v[0:1]
	v_pk_fma_f32 v[10:11], v[96:97], v[30:31], v[10:11]
	v_pk_fma_f32 v[8:9], v[98:99], v[28:29], v[8:9]
	v_cvt_pk_bf16_f32 v1, v10, v11
	v_cvt_pk_bf16_f32 v2, v2, v3
	v_cvt_pk_bf16_f32 v3, v26, v27
	v_pk_mul_f32 v[10:11], v[18:19], v[32:33] op_sel_hi:[1,0]
	v_cvt_pk_bf16_f32 v0, v8, v9
	global_store_dwordx4 v[34:35], v[0:3], off
	v_pk_mul_f32 v[8:9], v[16:17], v[32:33] op_sel_hi:[1,0]
	v_mov_b32_e32 v17, v224
	v_pk_mul_f32 v[0:1], v[20:21], v[32:33] op_sel_hi:[1,0]
	v_pk_mul_f32 v[2:3], v[22:23], v[32:33] op_sel_hi:[1,0]
	v_pk_fma_f32 v[0:1], v[90:91], v[0:1], v[12:13]
	v_pk_fma_f32 v[2:3], v[88:89], v[2:3], v[14:15]
	v_pk_fma_f32 v[6:7], v[84:85], v[10:11], v[6:7]
	v_pk_fma_f32 v[4:5], v[86:87], v[8:9], v[4:5]
	v_cvt_pk_bf16_f32 v0, v0, v1
	v_cvt_pk_bf16_f32 v1, v2, v3
	v_cvt_pk_bf16_f32 v3, v6, v7
	s_nop 0
	v_cvt_pk_bf16_f32 v2, v4, v5
	global_store_dwordx4 v[34:35], v[0:3], off offset:1024
	s_nop 0
	v_ashrrev_i32_e32 v16, 6, v17
	v_add_u32_e32 v64, s97, v16
	v_cmp_gt_i32_e32 vcc, s33, v64
	s_and_saveexec_b64 s[30:31], vcc
	s_cbranch_execz .LBB0_148
	v_lshlrev_b32_e32 v0, 3, v17
	v_and_b32_e32 v66, 0x1f8, v0
	v_lshlrev_b32_e32 v12, 2, v66
	global_load_dwordx4 v[0:3], v12, s[46:47] offset:16
	global_load_dwordx4 v[4:7], v12, s[46:47]
	global_load_dwordx4 v[8:11], v12, s[46:47] offset:2064
	s_nop 0
	global_load_dwordx4 v[12:15], v12, s[46:47] offset:2048
	s_add_i32 s0, s94, s95
	v_add_u32_e32 v16, s0, v16
	v_add_u32_e32 v72, 0x4000, v16
	v_and_b32_e32 v17, 63, v17
	v_ashrrev_i32_e32 v73, 31, v72
	s_lshl_b32 s46, s34, 5
	v_lshlrev_b32_e32 v70, 4, v17
	v_lshlrev_b64 v[16:17], 11, v[72:73]
	v_ashrrev_i32_e32 v65, 31, v64
	v_or_b32_e32 v18, 0x200, v66
	v_lshlrev_b32_e32 v80, 1, v66
	v_lshl_add_u64 v[74:75], s[58:59], 0, v[16:17]
	s_ashr_i32 s47, s46, 31
	v_lshlrev_b64 v[16:17], 11, v[64:65]
	v_lshl_add_u64 v[68:69], s[26:27], 0, v[80:81]
	s_lshl_b32 s60, s34, 4
	s_mul_i32 s61, s34, 24
	v_mov_b32_e32 v71, v81
	s_lshl_b64 s[48:49], s[46:47], 11
	v_lshl_add_u64 v[76:77], s[58:59], 0, v[16:17]
	s_mov_b64 s[50:51], 0
	s_mov_b32 s66, 0x1a70000
	v_lshlrev_b32_e32 v78, 2, v18
	s_movk_i32 s67, 0x407f
	s_mov_b64 s[52:53], 0
	v_mov_b32_e32 v67, v64
	s_branch .LBB0_136

; __device__ __forceinline__ float bf_lo(unsigned u) { return __uint_as_float(u << 16); }
; __device__ __forceinline__ float bf_hi(unsigned u) { return __uint_as_float(u & 0xffff0000u); }
;     __device__ __forceinline__ void fused(f32x4 (&acc)[2][2][4][2], const Unit& u, int wr, int wc, int fr, int fq, float* smem) const {
;     ...
;         const float* mb = mod + (size_t)(u.pm >> 3) * NMOD;
;         const int cb = u.pn * BM + wc * 32 + 8 * fq, rl0 = wr * 64 + fr;
;         float* part = smem; float* rsv = smem + 1024;
;         f32x4 gt[2][2];
; #pragma unroll
;         for (int bj = 0; bj < 2; ++bj)
; #pragma unroll
;             for (int n = 0; n < 2; ++n) gt[bj][n] = *(const f32x4*)(mb + (MODE ? 5120 : 2048) + cb + bj * HALF + n * 4);
; #pragma unroll
;         for (int ai = 0; ai < 2; ++ai) {
;             f32x4 bs[4][2][2];
; #pragma unroll
;             for (int m = 0; m < 4; ++m) { const size_t ro = (size_t)(u.pm * BM + rl0 + ai * HALF + m * 16) * DM;
; #pragma unroll
;                 for (int bj = 0; bj < 2; ++bj)
; #pragma unroll
;                     for (int n = 0; n < 2; ++n) { const int c = cb + bj * HALF + n * 4;
;                         if (MODE) { const uint2 q = *(const uint2*)(X1 + ro + c); bs[m][bj][n] = (f32x4){bf_lo(q.x), bf_hi(q.x), bf_lo(q.y), bf_hi(q.y)}; }
;                         else bs[m][bj][n] = *(const f32x4*)(xp + ro + c); } }
;             __builtin_amdgcn_sched_barrier(0);
; #pragma unroll
;             for (int m = 0; m < 4; ++m) { float ss = 0.f;
; #pragma unroll
;                 for (int bj = 0; bj < 2; ++bj)
; #pragma unroll
;                     for (int n = 0; n < 2; ++n) { const f32x4 v = bs[m][bj][n] + gt[bj][n] * acc[ai][bj][m][n]; acc[ai][bj][m][n] = v; ss += v[0] * v[0] + v[1] * v[1] + v[2] * v[2] + v[3] * v[3]; }
;                 ss += __shfl_xor(ss, 16); ss += __shfl_xor(ss, 32);
;                 if (fq == 0) part[(rl0 + ai * HALF + m * 16) * 4 + wc] = ss; } }
.LBB0_535:
	s_ashr_i32 s0, s8, 3
	s_lshl_b32 s4, s33, 5
	s_mul_hi_i32 s1, s0, 0x6000
	s_mulk_i32 s0, 0x6000
	s_add_u32 s0, s16, s0
	s_addc_u32 s1, s17, s1
	s_lshl_b32 s5, s9, 8
	s_or_b32 s4, s5, s4
	v_lshl_or_b32 v194, v196, 3, s4
	v_ashrrev_i32_e32 v195, 31, v194
	v_lshlrev_b64 v[222:223], 2, v[194:195]
	v_lshl_add_u64 v[128:129], s[0:1], 0, v[222:223]
	s_mov_b64 s[4:5], 0x2000
	v_lshl_add_u64 v[132:133], v[128:129], 0, s[4:5]
	s_movk_i32 s4, 0x2000
	v_add_co_u32_e32 v128, vcc, s4, v128
	s_lshl_b32 s4, s8, 8
	v_add_u32_e32 v192, s4, v231
	v_ashrrev_i32_e32 v193, 31, v192
	v_lshlrev_b64 v[144:145], 12, v[192:193]
	v_lshl_add_u64 v[144:145], s[36:37], 0, v[144:145]
	v_mov_b32_e32 v202, v224
	v_addc_co_u32_e32 v129, vcc, 0, v129, vcc
	v_lshl_add_u64 v[144:145], v[144:145], 0, v[222:223]
	s_barrier
	global_load_dwordx4 v[140:143], v[128:129], off
	s_nop 0
	global_load_dwordx4 v[128:131], v[132:133], off offset:528
	global_load_dwordx4 v[136:139], v[132:133], off offset:16
	s_nop 0
	global_load_dwordx4 v[132:135], v[132:133], off offset:512
	s_nop 0
	global_load_dwordx4 v[198:201], v[144:145], off offset:16 nt
	global_load_dwordx4 v[204:207], v[144:145], off nt
	global_load_dwordx4 v[232:235], v[144:145], off offset:528 nt
	global_load_dwordx4 v[208:211], v[144:145], off offset:512 nt
	v_or_b32_e32 v144, 16, v192
	v_ashrrev_i32_e32 v145, 31, v144
	v_lshlrev_b64 v[144:145], 12, v[144:145]
	v_lshl_add_u64 v[144:145], s[36:37], 0, v[144:145]
	v_lshl_add_u64 v[144:145], v[144:145], 0, v[222:223]
	global_load_dwordx4 v[184:187], v[144:145], off offset:16 nt
	global_load_dwordx4 v[188:191], v[144:145], off nt
	global_load_dwordx4 v[176:179], v[144:145], off offset:528 nt
	global_load_dwordx4 v[180:183], v[144:145], off offset:512 nt
	v_or_b32_e32 v144, 32, v192
	v_ashrrev_i32_e32 v145, 31, v144
	v_lshlrev_b64 v[144:145], 12, v[144:145]
	v_lshl_add_u64 v[144:145], s[36:37], 0, v[144:145]
	v_lshl_add_u64 v[144:145], v[144:145], 0, v[222:223]
	global_load_dwordx4 v[168:171], v[144:145], off offset:16 nt
	global_load_dwordx4 v[172:175], v[144:145], off nt
	global_load_dwordx4 v[160:163], v[144:145], off offset:528 nt
	global_load_dwordx4 v[164:167], v[144:145], off offset:512 nt
	v_or_b32_e32 v144, 48, v192
	v_ashrrev_i32_e32 v145, 31, v144
	v_lshlrev_b64 v[144:145], 12, v[144:145]
	v_lshl_add_u64 v[144:145], s[36:37], 0, v[144:145]
	v_lshl_add_u64 v[148:149], v[144:145], 0, v[222:223]
	global_load_dwordx4 v[152:155], v[148:149], off offset:16 nt
	global_load_dwordx4 v[156:159], v[148:149], off nt
	global_load_dwordx4 v[144:147], v[148:149], off offset:528 nt
	s_nop 0
	global_load_dwordx4 v[148:151], v[148:149], off offset:512 nt
	s_lshl_b32 s4, s33, 2
	s_add_i32 s4, s4, 16
	v_cmp_eq_u32_e32 vcc, 0, v196
	v_lshl_add_u32 v203, v231, 4, s4
	s_waitcnt vmcnt(0)
	v_pk_fma_f32 v[216:217], v[124:125], v[140:141], v[204:205]
	v_pk_fma_f32 v[220:221], v[120:121], v[136:137], v[198:199]
	v_mul_f32_e32 v124, v217, v217
	v_mul_f32_e32 v120, v221, v221
	v_pk_fma_f32 v[208:209], v[116:117], v[132:133], v[208:209]
	v_pk_fma_f32 v[214:215], v[126:127], v[142:143], v[206:207]
	v_fmac_f32_e32 v124, v216, v216
	v_pk_fma_f32 v[218:219], v[122:123], v[138:139], v[200:201]
	v_fmac_f32_e32 v120, v220, v220
	v_mul_f32_e32 v116, v209, v209
	v_pk_fma_f32 v[212:213], v[108:109], v[128:129], v[232:233]
	v_fmac_f32_e32 v124, v214, v214
	v_fmac_f32_e32 v120, v218, v218
	v_pk_fma_f32 v[206:207], v[118:119], v[134:135], v[210:211]
	v_fmac_f32_e32 v116, v208, v208
	v_mul_f32_e32 v108, v213, v213
	v_fmac_f32_e32 v124, v215, v215
	v_fmac_f32_e32 v120, v219, v219
	v_fmac_f32_e32 v116, v206, v206
	v_pk_fma_f32 v[210:211], v[110:111], v[130:131], v[234:235]
	v_fmac_f32_e32 v108, v212, v212
	v_add_f32_e32 v120, v124, v120
	v_fmac_f32_e32 v116, v207, v207
	v_fmac_f32_e32 v108, v210, v210
	v_add_f32_e32 v116, v120, v116
	v_fmac_f32_e32 v108, v211, v211
	v_add_f32_e32 v108, v116, v108
	ds_bpermute_b32 v109, v229, v108
	s_waitcnt lgkmcnt(0)
	v_add_f32_e32 v108, v108, v109
	ds_bpermute_b32 v109, v230, v108
	s_and_saveexec_b64 s[4:5], vcc
	s_cbranch_execz .LBB0_537
	s_waitcnt lgkmcnt(0)
	v_add_f32_e32 v108, v108, v109
	ds_write_b32 v203, v108

; __device__ __forceinline__ float bf_lo(unsigned u) { return __uint_as_float(u << 16); }
; __device__ __forceinline__ float bf_hi(unsigned u) { return __uint_as_float(u & 0xffff0000u); }
;     __device__ __forceinline__ void fused(f32x4 (&acc)[2][2][4][2], const Unit& u, int wr, int wc, int fr, int fq, float* smem) const {
;     ...
;         for (int ai = 0; ai < 2; ++ai) {
;             f32x4 bs[4][2][2];
; #pragma unroll
;             for (int m = 0; m < 4; ++m) { const size_t ro = (size_t)(u.pm * BM + rl0 + ai * HALF + m * 16) * DM;
; #pragma unroll
;                 for (int bj = 0; bj < 2; ++bj)
; #pragma unroll
;                     for (int n = 0; n < 2; ++n) { const int c = cb + bj * HALF + n * 4;
;                         if (MODE) { const uint2 q = *(const uint2*)(X1 + ro + c); bs[m][bj][n] = (f32x4){bf_lo(q.x), bf_hi(q.x), bf_lo(q.y), bf_hi(q.y)}; }
;                         else bs[m][bj][n] = *(const f32x4*)(xp + ro + c); } }
;             __builtin_amdgcn_sched_barrier(0);
; #pragma unroll
;             for (int m = 0; m < 4; ++m) { float ss = 0.f;
; #pragma unroll
;                 for (int bj = 0; bj < 2; ++bj)
; #pragma unroll
;                     for (int n = 0; n < 2; ++n) { const f32x4 v = bs[m][bj][n] + gt[bj][n] * acc[ai][bj][m][n]; acc[ai][bj][m][n] = v; ss += v[0] * v[0] + v[1] * v[1] + v[2] * v[2] + v[3] * v[3]; }
;                 ss += __shfl_xor(ss, 16); ss += __shfl_xor(ss, 32);
;                 if (fq == 0) part[(rl0 + ai * HALF + m * 16) * 4 + wc] = ss; } }
.LBB0_543:
	s_or_b64 exec, exec, s[4:5]
	v_add_u32_e32 v124, 0x80, v192
	v_ashrrev_i32_e32 v125, 31, v124
	s_waitcnt lgkmcnt(0)
	v_lshlrev_b64 v[64:65], 12, v[124:125]
	v_lshl_add_u64 v[64:65], s[36:37], 0, v[64:65]
	v_add_u32_e32 v116, 0x90, v192
	v_lshl_add_u64 v[64:65], v[64:65], 0, v[222:223]
	v_ashrrev_i32_e32 v117, 31, v116
	global_load_dwordx4 v[144:147], v[64:65], off offset:16 nt
	global_load_dwordx4 v[148:151], v[64:65], off nt
	global_load_dwordx4 v[232:235], v[64:65], off offset:528 nt
	global_load_dwordx4 v[236:239], v[64:65], off offset:512 nt
	v_lshlrev_b64 v[64:65], 12, v[116:117]
	v_lshl_add_u64 v[64:65], s[36:37], 0, v[64:65]
	v_add_u32_e32 v114, 0xa0, v192
	v_lshl_add_u64 v[64:65], v[64:65], 0, v[222:223]
	v_ashrrev_i32_e32 v115, 31, v114
	global_load_dwordx4 v[104:107], v[64:65], off offset:16 nt
	global_load_dwordx4 v[108:111], v[64:65], off nt
	global_load_dwordx4 v[96:99], v[64:65], off offset:528 nt
	global_load_dwordx4 v[100:103], v[64:65], off offset:512 nt
	v_lshlrev_b64 v[64:65], 12, v[114:115]
	v_lshl_add_u64 v[64:65], s[36:37], 0, v[64:65]
	v_add_u32_e32 v112, 0xb0, v192
	v_lshl_add_u64 v[64:65], v[64:65], 0, v[222:223]
	v_ashrrev_i32_e32 v113, 31, v112
	global_load_dwordx4 v[88:91], v[64:65], off offset:16 nt
	global_load_dwordx4 v[92:95], v[64:65], off nt
	global_load_dwordx4 v[80:83], v[64:65], off offset:528 nt
	global_load_dwordx4 v[84:87], v[64:65], off offset:512 nt
	v_lshlrev_b64 v[64:65], 12, v[112:113]
	v_lshl_add_u64 v[64:65], s[36:37], 0, v[64:65]
	v_lshl_add_u64 v[68:69], v[64:65], 0, v[222:223]
	global_load_dwordx4 v[72:75], v[68:69], off offset:16 nt
	global_load_dwordx4 v[76:79], v[68:69], off nt
	global_load_dwordx4 v[64:67], v[68:69], off offset:528 nt
	s_nop 0
	global_load_dwordx4 v[68:71], v[68:69], off offset:512 nt
	s_waitcnt vmcnt(14)
	v_pk_fma_f32 v[168:169], v[60:61], v[140:141], v[148:149]
	v_pk_fma_f32 v[180:181], v[56:57], v[136:137], v[144:145]
	v_mul_f32_e32 v60, v169, v169
	v_pk_fma_f32 v[176:177], v[58:59], v[138:139], v[146:147]
	v_mul_f32_e32 v56, v181, v181
	s_waitcnt vmcnt(12)
	v_pk_fma_f32 v[146:147], v[52:53], v[132:133], v[236:237]
	v_pk_fma_f32 v[160:161], v[62:63], v[142:143], v[150:151]
	v_fmac_f32_e32 v60, v168, v168
	v_fmac_f32_e32 v56, v180, v180
	v_mul_f32_e32 v52, v147, v147
	v_pk_fma_f32 v[150:151], v[44:45], v[128:129], v[232:233]
	v_fmac_f32_e32 v60, v160, v160
	v_fmac_f32_e32 v56, v176, v176
	v_pk_fma_f32 v[144:145], v[54:55], v[134:135], v[238:239]
	v_fmac_f32_e32 v52, v146, v146
	v_mul_f32_e32 v44, v151, v151
	v_fmac_f32_e32 v60, v161, v161
	v_fmac_f32_e32 v56, v177, v177
	v_fmac_f32_e32 v52, v144, v144
	v_pk_fma_f32 v[148:149], v[46:47], v[130:131], v[234:235]
	v_fmac_f32_e32 v44, v150, v150
	v_add_f32_e32 v56, v60, v56
	v_fmac_f32_e32 v52, v145, v145
	v_fmac_f32_e32 v44, v148, v148
	v_add_f32_e32 v52, v56, v52
	v_fmac_f32_e32 v44, v149, v149
	v_add_f32_e32 v44, v52, v44
	ds_bpermute_b32 v45, v229, v44
	s_waitcnt lgkmcnt(0)
	v_add_f32_e32 v44, v44, v45
	ds_bpermute_b32 v45, v230, v44
	s_and_saveexec_b64 s[4:5], vcc
	s_cbranch_execz .LBB0_545
	s_waitcnt lgkmcnt(0)
	v_add_f32_e32 v44, v44, v45
	ds_write_b32 v203, v44 offset:2048
